# v42 + As[1][1]@1 DMAs of the next unit hoisted above the epilogue stores (G1, G4): stores first forced at wait 4 instead of wait 3
# baseline (speedup 1.0000x reference)
; #define PG8_STAGE(bufoff, gbase, voff) do { _Pragma("unroll") for (int _i = 0; _i < 2; ++_i) \
;         __builtin_amdgcn_global_load_lds((const unsigned*)((const char*)(gbase) + (voff)[_i]), (PG8_LAS unsigned*)(lds + (bufoff) + ldsw + _i * 8192), 16, 0, 0); } while (0)
; #define PG8_WAIT_V(n) asm volatile("s_waitcnt vmcnt(" #n ")" ::: "memory")
; #define PG8_BAR __builtin_amdgcn_s_barrier()
; template <class Epi, class Sched, bool ALIGN_EPI = false, bool SP2 = false, bool KHOOK = false>
; __device__ __forceinline__ void gemm_phase(PG8_LAS unsigned char* lds, const Gemm g, const Sched& S, const Epi& E, const int tid_in) {
;     ...
;     for (int i = 0; i < 2; ++i) { int R, C; stage_rc(tid * 16 + i * 8192, R, C); const int Rb = Epi::PERM ? ((R & ~31) + perm32(R & 31)) : R;
;         voffA[i] = (unsigned)(R * LD + C) * 2u; voffB[i] = (unsigned)(Rb * LD + C) * 2u; }
;     const size_t kstep = (size_t)(BK * 2);
;     const size_t hstep = (size_t)HALF * LD * 2;
;     const size_t tstep = 2 * hstep;
;     const unsigned ldsw = (unsigned)wid * 1024u;
;     const int aoff = lds_byte(wr * 64 + fr, fq * 8), boff = lds_byte(wc * 32 + fr, fq * 8);
;     ...
;     if constexpr (SP2) {
;         PG8_STAGE(PG8_SB(0, 0), cB, voffB); PG8_STAGE(PG8_SB(0, 1), cB + hstep, voffB); PG8_STAGE(PG8_SA(0, 0), cA, voffA); PG8_STAGE(PG8_SA(0, 1), cA + hstep, voffA);
;         if (wr == 1) PG8_BAR;
;         PG8_WAIT_V(2); PG8_BAR;
;         PG8_STAGE(PG8_SB(1, 0), cB + kstep, voffB); PG8_STAGE(PG8_SA(1, 0), cA + kstep, voffA); PG8_STAGE(PG8_SB(1, 1), cB + hstep + kstep, voffB);
;         PG8_WAIT_V(6); PG8_BAR;
.LBB0_256:
	v_lshrrev_b32_e32 v16, 1, v6
	v_and_b32_e32 v16, 24, v16
	v_and_b32_e32 v7, 15, v6
	v_lshlrev_b32_e32 v17, 1, v16
	v_lshlrev_b32_e32 v6, 2, v6
	v_lshl_or_b32 v140, s14, 6, v7
	v_lshl_or_b32 v7, v7, 6, v17
	s_lshl_b32 s11, s14, 13
	v_and_b32_e32 v6, 32, v6
	s_lshl_b32 s9, s9, 5
	v_bitop3_b32 v17, v7, s11, v6 bitop3:0xde
	s_and_b32 s11, s9, 0x60
	v_lshl_add_u64 v[8:9], s[52:53], 0, v[32:33]
	v_mov_b32_e32 v135, v33
	s_lshl_b32 s9, s11, 7
	v_lshl_add_u64 v[10:11], s[52:53], 0, v[134:135]
	v_mov_b32_e32 v131, v33
	v_bitop3_b32 v141, s9, v7, v6 bitop3:0xf6
	s_add_i32 m0, s13, 0x18000
	v_lshl_add_u64 v[6:7], v[8:9], 0, s[90:91]
	v_lshl_add_u64 v[12:13], s[48:49], 0, v[130:131]
	v_mov_b32_e32 v133, v33
	global_load_lds_dwordx4 v[6:7], off
	v_lshl_add_u64 v[6:7], v[10:11], 0, s[90:91]
	s_add_i32 m0, s13, 0x1a000
	s_add_i32 s39, s13, 0x8000
	s_add_i32 s40, s13, 0xa000
	v_lshl_add_u64 v[14:15], s[48:49], 0, v[132:133]
	global_load_lds_dwordx4 v[6:7], off
	v_lshl_add_u64 v[6:7], v[12:13], 0, s[90:91]
	s_mov_b32 m0, s39
	s_add_u32 s14, s52, 0x80080
	global_load_lds_dwordx4 v[6:7], off
	v_lshl_add_u64 v[6:7], v[14:15], 0, s[90:91]
	s_mov_b32 m0, s40
	s_addc_u32 s15, s53, 0
	global_load_lds_dwordx4 v[6:7], off
	s_add_i32 m0, s13, 0x1c000
	v_lshl_add_u64 v[6:7], s[14:15], 0, v[32:33]
	global_load_lds_dwordx4 v[6:7], off
	v_lshl_add_u64 v[6:7], s[14:15], 0, v[134:135]
	s_add_i32 m0, s13, 0x1e000
	s_cmpk_lt_u32 s8, 0x100
	global_load_lds_dwordx4 v[6:7], off
	s_waitcnt vmcnt(2)
	s_barrier
	v_lshlrev_b32_e32 v6, 15, v0
	v_and_b32_e32 v6, 0xffff0000, v6
	v_lshl_add_u32 v1, v1, 12, v6
	v_and_b32_e32 v0, 1, v0
	v_lshl_or_b32 v0, v0, 6, v1
	v_lshl_add_u32 v136, v2, 1, v0
	v_lshlrev_b32_e32 v0, 15, v3
	v_and_b32_e32 v0, 0xffff0000, v0
	s_waitcnt vmcnt(6)
	v_lshl_add_u32 v0, v4, 12, v0
	v_and_b32_e32 v1, 1, v3
	v_lshl_or_b32 v0, v1, 6, v0
	s_cselect_b64 s[8:9], -1, 0
	v_or_b32_e32 v142, s11, v16
	v_mov_b32_e32 v137, v33
	v_lshl_add_u32 v138, v5, 1, v0
	v_mov_b32_e32 v139, v33
	s_mov_b32 s41, 0
	v_add_u32_e32 v143, 0, v17
	s_barrier
	s_waitcnt vmcnt(0)
	s_mov_b32 s60, 0
	s_branch .LBB0_259

; #define GPROBE_BEGIN(id) do { if (((PROBE_GEMM_SEL >> (id)) & 1) && blockIdx.x == 0 && tid_in < 64 && g.N == 20480) { volatile PG8_LAS unsigned long long* PW_ = (volatile PG8_LAS unsigned long long*)(lds + 163840 - 512 + 64); PW_[0] = __builtin_amdgcn_s_memrealtime(); } } while (0)
; #define GPROBE_END(id) do { if (((PROBE_GEMM_SEL >> (id)) & 1) && blockIdx.x == 0 && tid_in < 64 && g.N == 20480) { volatile PG8_LAS unsigned long long* PW_ = (volatile PG8_LAS unsigned long long*)(lds + 163840 - 512 + 64); PW_[1] += __builtin_amdgcn_s_memrealtime() - PW_[0]; } } while (0)
; #define PG8_STAGE(bufoff, gbase, voff) do { _Pragma("unroll") for (int _i = 0; _i < 2; ++_i) \
;         __builtin_amdgcn_global_load_lds((const unsigned*)((const char*)(gbase) + (voff)[_i]), (PG8_LAS unsigned*)(lds + (bufoff) + ldsw + _i * 8192), 16, 0, 0); } while (0)
; template <class Epi, class Sched, bool ALIGN_EPI = false, bool SP2 = false, bool KHOOK = false>
; __device__ __forceinline__ void gemm_phase(PG8_LAS unsigned char* lds, const Gemm g, const Sched& S, const Epi& E, const int tid_in) {
;     ...
;         const bool has_next = S.next(ui + 1, nxt);
;         const char* nA = has_next ? (const char*)g.A + (size_t)nxt.pm * tstep + (size_t)nxt.pn * ksl : cA; const char* nB = has_next ? (const char*)g.Bt + (size_t)nxt.pn * bts + (size_t)nxt.pn * ksl + (gdv ? (size_t)(nxt.pm / gdv) * gst : 0) : cB;
;         GPROBE_END(2); GPROBE_BEGIN(1);
;         for (int t = 0; t < nt; t += 2) {
;             const bool last = (t == nt - 2);
;             const char* a1 = cA + (size_t)(t + 1) * kstep;
;             const char* a2 = last ? nA : cA + (size_t)(t + 2) * kstep; const char* b2 = last ? nB : cB + (size_t)(t + 2) * kstep;
;             const char* a3 = a2 + kstep; const char* b3 = b2 + kstep;
;             if (last && has_next) S.a_ready(nxt);
;             if constexpr (SP2) {
;             PG8_LDB(B0, 0, 0); PG8_LDB(B1, 0, 1); PG8_SCHED; PG8_LDA(At, 0, 0); PG8_STAGE(PG8_SA(1, 1), a1 + hstep, voffA);
;             PG8_WAIT_V(8); PG8_WAIT_L(0); PG8_BAR; PG8_MMA(0, 0, At, B0); PG8_MMA(0, 1, At, B1); PG8_BAR; PG8_SCHED;
;             PG8_LDA(At, 0, 1); PG8_STAGE(PG8_SB(0, 0), b2, voffB); PG8_STAGE(PG8_SB(0, 1), b2 + hstep, voffB); PG8_STAGE(PG8_SA(0, 0), a2, voffA);
;             PG8_WAIT_V(8); PG8_WAIT_L(0); PG8_BAR; PG8_MMA(1, 0, At, B0); PG8_MMA(1, 1, At, B1); PG8_BAR; PG8_SCHED;
.LBB0_262:
	s_ashr_i32 s17, s16, 31
	s_lshl_b64 s[18:19], s[16:17], 20
	s_add_u32 s26, s78, s18
	s_addc_u32 s27, s79, s19
	s_and_b64 s[18:19], s[22:23], exec
	s_cselect_b32 s11, s27, s49
	s_cselect_b32 s17, s26, s48
	s_ashr_i32 s15, s14, 31
	s_lshl_b64 s[18:19], s[14:15], 20
	v_readlane_b32 s5, v255, 25
	s_add_u32 s30, s5, s18
	v_readlane_b32 s5, v255, 26
	s_addc_u32 s31, s5, s19
	s_and_b64 s[18:19], s[22:23], exec
	s_cselect_b32 s15, s31, s53
	s_cselect_b32 s18, s30, s52
	s_add_u32 s48, s48, 0x80080
	s_addc_u32 s49, s49, 0
	s_add_u32 s19, s52, 0x100
	s_addc_u32 s42, s53, 0
	s_mov_b32 s44, -2
	s_cmp_lg_u32 s60, 0
	s_cbranch_scc1 .Lg1_peel_h
	s_add_u32 s45, s48, 0xfff80080
	s_addc_u32 s46, s49, -1
	s_add_i32 s47, 0, 0x10000
	s_cmp_eq_u32 s44, 28
	s_cselect_b32 s57, s11, s46
	s_cselect_b32 s56, s17, s45
	s_cselect_b32 s53, s15, s42
	s_cselect_b32 s52, s18, s19
	s_add_i32 s45, 0, 0x14000
	v_add_u32_e32 v156, s47, v141
	v_add_u32_e32 v172, s45, v141
	ds_read_b128 v[144:147], v156
	ds_read_b128 v[148:151], v156 offset:1024
	ds_read_b128 v[152:155], v156 offset:2048
	ds_read_b128 v[156:159], v156 offset:3072
	ds_read_b128 v[160:163], v172
	ds_read_b128 v[164:167], v172 offset:1024
	ds_read_b128 v[168:171], v172 offset:2048
	ds_read_b128 v[172:175], v172 offset:3072
	v_lshl_add_u64 v[192:193], s[48:49], 0, v[136:137]
	s_add_i32 m0, s13, 0xc000
	ds_read_b128 v[176:179], v143
	ds_read_b128 v[180:183], v143 offset:1024
	ds_read_b128 v[184:187], v143 offset:2048
	ds_read_b128 v[188:191], v143 offset:3072
	ds_read_b128 v[198:201], v143 offset:4096
	ds_read_b128 v[202:205], v143 offset:5120
	ds_read_b128 v[206:209], v143 offset:6144
	ds_read_b128 v[210:213], v143 offset:7168
	global_load_lds_dwordx4 v[192:193], off
	v_lshl_add_u64 v[192:193], s[48:49], 0, v[138:139]
	s_add_i32 m0, s13, 0xe000
	s_nop 0
	global_load_lds_dwordx4 v[192:193], off
	s_waitcnt vmcnt(18)
	s_waitcnt lgkmcnt(0)
	s_barrier
	s_setprio 1
	s_waitcnt lgkmcnt(0)
	v_mfma_f32_16x16x32_bf16 v[126:129], v[144:147], v[176:179], 0
	v_mfma_f32_16x16x32_bf16 v[122:125], v[152:155], v[176:179], 0
	v_mfma_f32_16x16x32_bf16 v[118:121], v[144:147], v[184:187], 0
	v_mfma_f32_16x16x32_bf16 v[114:117], v[152:155], v[184:187], 0
	v_mfma_f32_16x16x32_bf16 v[102:105], v[144:147], v[198:201], 0
	v_mfma_f32_16x16x32_bf16 v[98:101], v[152:155], v[198:201], 0
	v_mfma_f32_16x16x32_bf16 v[86:89], v[144:147], v[206:209], 0
	v_mfma_f32_16x16x32_bf16 v[82:85], v[152:155], v[206:209], 0
	v_mfma_f32_16x16x32_bf16 v[126:129], v[148:151], v[180:183], v[126:129]
	v_mfma_f32_16x16x32_bf16 v[122:125], v[156:159], v[180:183], v[122:125]
	v_mfma_f32_16x16x32_bf16 v[118:121], v[148:151], v[188:191], v[118:121]
	v_mfma_f32_16x16x32_bf16 v[114:117], v[156:159], v[188:191], v[114:117]
	v_mfma_f32_16x16x32_bf16 v[102:105], v[148:151], v[202:205], v[102:105]
	v_mfma_f32_16x16x32_bf16 v[98:101], v[156:159], v[202:205], v[98:101]
	v_mfma_f32_16x16x32_bf16 v[86:89], v[148:151], v[210:213], v[86:89]
	v_mfma_f32_16x16x32_bf16 v[82:85], v[156:159], v[210:213], v[82:85]
	s_setprio 0
	s_setprio 1
	v_mfma_f32_16x16x32_bf16 v[110:113], v[160:163], v[176:179], 0
	v_mfma_f32_16x16x32_bf16 v[106:109], v[168:171], v[176:179], 0
	v_mfma_f32_16x16x32_bf16 v[94:97], v[160:163], v[184:187], 0
	v_mfma_f32_16x16x32_bf16 v[90:93], v[168:171], v[184:187], 0
	v_mfma_f32_16x16x32_bf16 v[78:81], v[160:163], v[198:201], 0
	v_mfma_f32_16x16x32_bf16 v[74:77], v[168:171], v[198:201], 0
	v_mfma_f32_16x16x32_bf16 v[70:73], v[160:163], v[206:209], 0
	v_mfma_f32_16x16x32_bf16 v[66:69], v[168:171], v[206:209], 0
	v_mfma_f32_16x16x32_bf16 v[110:113], v[164:167], v[180:183], v[110:113]
	v_mfma_f32_16x16x32_bf16 v[106:109], v[172:175], v[180:183], v[106:109]
	v_mfma_f32_16x16x32_bf16 v[94:97], v[164:167], v[188:191], v[94:97]
	v_mfma_f32_16x16x32_bf16 v[90:93], v[172:175], v[188:191], v[90:93]
	v_mfma_f32_16x16x32_bf16 v[78:81], v[164:167], v[202:205], v[78:81]
	v_mfma_f32_16x16x32_bf16 v[74:77], v[172:175], v[202:205], v[74:77]
	v_mfma_f32_16x16x32_bf16 v[70:73], v[164:167], v[210:213], v[70:73]
	v_mfma_f32_16x16x32_bf16 v[66:69], v[172:175], v[210:213], v[66:69]
	s_setprio 0
	s_barrier
	s_add_i32 s46, s47, s37
	v_lshl_add_u64 v[192:193], s[52:53], 0, v[32:33]
	s_mov_b32 m0, s46
	ds_read_b128 v[176:179], v143 offset:16384
	ds_read_b128 v[180:183], v143 offset:17408
	ds_read_b128 v[184:187], v143 offset:18432
	ds_read_b128 v[188:191], v143 offset:19456
	ds_read_b128 v[198:201], v143 offset:20480
	ds_read_b128 v[202:205], v143 offset:21504
	ds_read_b128 v[206:209], v143 offset:22528
	ds_read_b128 v[210:213], v143 offset:23552
	global_load_lds_dwordx4 v[192:193], off
	s_add_i32 m0, s46, 0x2000
	s_add_u32 s46, s52, 0x80000
	v_lshl_add_u64 v[214:215], s[52:53], 0, v[134:135]
	s_addc_u32 s47, s53, 0
	s_add_i32 s45, s45, s37
	global_load_lds_dwordx4 v[214:215], off
	v_lshl_add_u64 v[216:217], s[46:47], 0, v[32:33]
	s_mov_b32 m0, s45
	v_lshl_add_u64 v[218:219], s[56:57], 0, v[132:133]
	global_load_lds_dwordx4 v[216:217], off
	v_lshl_add_u64 v[216:217], s[46:47], 0, v[134:135]
	s_add_i32 m0, s45, 0x2000
	s_nop 0
	global_load_lds_dwordx4 v[216:217], off
	v_lshl_add_u64 v[216:217], s[56:57], 0, v[130:131]
	s_mov_b32 m0, s13
	s_nop 0
	global_load_lds_dwordx4 v[216:217], off
	s_mov_b32 m0, s24
	s_nop 0
	global_load_lds_dwordx4 v[218:219], off
	s_waitcnt vmcnt(24)
	s_waitcnt lgkmcnt(0)
	s_barrier
; #define PG8_STAGE(bufoff, gbase, voff) do { _Pragma("unroll") for (int _i = 0; _i < 2; ++_i) \
;         __builtin_amdgcn_global_load_lds((const unsigned*)((const char*)(gbase) + (voff)[_i]), (PG8_LAS unsigned*)(lds + (bufoff) + ldsw + _i * 8192), 16, 0, 0); } while (0)
; #define PG8_LDA(dst, b, h) do { _Pragma("unroll") for (int m = 0; m < 4; ++m) _Pragma("unroll") for (int k = 0; k < 2; ++k) dst[m][k] = *(const PG8_LAS bf16x8*)(lds + PG8_SA(b, h) + aoff + m * 2048 + k * 1024); } while (0)
; #define PG8_LDB(dst, b, h) do { _Pragma("unroll") for (int n = 0; n < 2; ++n) _Pragma("unroll") for (int k = 0; k < 2; ++k) dst[n][k] = *(const PG8_LAS bf16x8*)(lds + PG8_SB(b, h) + boff + n * 2048 + k * 1024); } while (0)
; #define PG8_MMA(ai, bj, At, Bt) do { __builtin_amdgcn_s_setprio(1); _Pragma("unroll") for (int m = 0; m < 4; ++m) _Pragma("unroll") for (int n = 0; n < 2; ++n) _Pragma("unroll") for (int k = 0; k < 2; ++k) \
;         acc[ai][bj][m][n] = __builtin_amdgcn_mfma_f32_16x16x32_bf16(Bt[n][k], At[m][k], acc[ai][bj][m][n], 0, 0, 0); __builtin_amdgcn_s_setprio(0); } while (0)
; #define PG8_WAIT_V(n) asm volatile("s_waitcnt vmcnt(" #n ")" ::: "memory")
; #define PG8_WAIT_L(n) asm volatile("s_waitcnt lgkmcnt(" #n ")" ::: "memory")
; #define PG8_BAR __builtin_amdgcn_s_barrier()
; #define PG8_SCHED __builtin_amdgcn_sched_barrier(0)
; template <class Epi, class Sched, bool ALIGN_EPI = false, bool SP2 = false, bool KHOOK = false>
; __device__ __forceinline__ void gemm_phase(PG8_LAS unsigned char* lds, const Gemm g, const Sched& S, const Epi& E, const int tid_in) {
;     ...
;             PG8_LDA(At, 0, 1); PG8_STAGE(PG8_SB(0, 0), b2, voffB); PG8_STAGE(PG8_SB(0, 1), b2 + hstep, voffB); PG8_STAGE(PG8_SA(0, 0), a2, voffA);
;             PG8_WAIT_V(8); PG8_WAIT_L(0); PG8_BAR; PG8_MMA(1, 0, At, B0); PG8_MMA(1, 1, At, B1); PG8_BAR; PG8_SCHED;
;             PG8_LDB(B0, 1, 0); PG8_LDB(B1, 1, 1); PG8_SCHED; PG8_LDA(At, 1, 0); PG8_STAGE(PG8_SA(0, 1), a2 + hstep, voffA);
;             PG8_WAIT_V(8); PG8_WAIT_L(0); PG8_BAR; PG8_MMA(0, 0, At, B0); PG8_MMA(0, 1, At, B1); PG8_BAR; PG8_SCHED;
	s_setprio 1
	s_waitcnt lgkmcnt(0)
	v_mfma_f32_16x16x32_bf16 v[62:65], v[144:147], v[176:179], 0
	v_mfma_f32_16x16x32_bf16 v[58:61], v[152:155], v[176:179], 0
	v_mfma_f32_16x16x32_bf16 v[54:57], v[144:147], v[184:187], 0
	v_mfma_f32_16x16x32_bf16 v[50:53], v[152:155], v[184:187], 0
	v_mfma_f32_16x16x32_bf16 v[38:41], v[144:147], v[198:201], 0
	v_mfma_f32_16x16x32_bf16 v[34:37], v[152:155], v[198:201], 0
	v_mfma_f32_16x16x32_bf16 v[20:23], v[144:147], v[206:209], 0
	v_mfma_f32_16x16x32_bf16 v[16:19], v[152:155], v[206:209], 0
	v_mfma_f32_16x16x32_bf16 v[62:65], v[148:151], v[180:183], v[62:65]
	v_mfma_f32_16x16x32_bf16 v[58:61], v[156:159], v[180:183], v[58:61]
	v_mfma_f32_16x16x32_bf16 v[54:57], v[148:151], v[188:191], v[54:57]
	v_mfma_f32_16x16x32_bf16 v[50:53], v[156:159], v[188:191], v[50:53]
	v_mfma_f32_16x16x32_bf16 v[38:41], v[148:151], v[202:205], v[38:41]
	v_mfma_f32_16x16x32_bf16 v[34:37], v[156:159], v[202:205], v[34:37]
	v_mfma_f32_16x16x32_bf16 v[20:23], v[148:151], v[210:213], v[20:23]
	v_mfma_f32_16x16x32_bf16 v[16:19], v[156:159], v[210:213], v[16:19]
	s_setprio 0
	s_setprio 1
	v_mfma_f32_16x16x32_bf16 v[46:49], v[160:163], v[176:179], 0
	v_mfma_f32_16x16x32_bf16 v[42:45], v[168:171], v[176:179], 0
	v_mfma_f32_16x16x32_bf16 v[28:31], v[160:163], v[184:187], 0
	v_mfma_f32_16x16x32_bf16 v[24:27], v[168:171], v[184:187], 0
	v_mfma_f32_16x16x32_bf16 v[12:15], v[160:163], v[198:201], 0
	v_mfma_f32_16x16x32_bf16 v[8:11], v[168:171], v[198:201], 0
	v_mfma_f32_16x16x32_bf16 v[4:7], v[160:163], v[206:209], 0
	v_mfma_f32_16x16x32_bf16 v[0:3], v[168:171], v[206:209], 0
	v_mfma_f32_16x16x32_bf16 v[46:49], v[164:167], v[180:183], v[46:49]
	v_mfma_f32_16x16x32_bf16 v[42:45], v[172:175], v[180:183], v[42:45]
	v_mfma_f32_16x16x32_bf16 v[28:31], v[164:167], v[188:191], v[28:31]
	v_mfma_f32_16x16x32_bf16 v[24:27], v[172:175], v[188:191], v[24:27]
	v_mfma_f32_16x16x32_bf16 v[12:15], v[164:167], v[202:205], v[12:15]
	v_mfma_f32_16x16x32_bf16 v[8:11], v[172:175], v[202:205], v[8:11]
	v_mfma_f32_16x16x32_bf16 v[4:7], v[164:167], v[210:213], v[4:7]
	v_mfma_f32_16x16x32_bf16 v[0:3], v[172:175], v[210:213], v[0:3]
	s_setprio 0
	s_barrier
	s_add_i32 s45, 0, 0x18000
	s_add_i32 s50, 0, 0x1c000
	v_add_u32_e32 v156, s45, v141
	v_add_u32_e32 v172, s50, v141
	ds_read_b128 v[144:147], v156
	ds_read_b128 v[148:151], v156 offset:1024
	ds_read_b128 v[152:155], v156 offset:2048
	ds_read_b128 v[156:159], v156 offset:3072
	ds_read_b128 v[160:163], v172
	ds_read_b128 v[164:167], v172 offset:1024
	ds_read_b128 v[168:171], v172 offset:2048
	ds_read_b128 v[172:175], v172 offset:3072
	s_add_u32 s46, s56, 0x80000
	s_addc_u32 s47, s57, 0
	s_mov_b32 m0, s25
	v_lshl_add_u64 v[220:221], s[46:47], 0, v[130:131]
	ds_read_b128 v[176:179], v143 offset:32768
	ds_read_b128 v[180:183], v143 offset:33792
	ds_read_b128 v[184:187], v143 offset:34816
	ds_read_b128 v[188:191], v143 offset:35840
	ds_read_b128 v[198:201], v143 offset:36864
	ds_read_b128 v[202:205], v143 offset:37888
	ds_read_b128 v[206:209], v143 offset:38912
	ds_read_b128 v[210:213], v143 offset:39936
	global_load_lds_dwordx4 v[220:221], off
	v_lshl_add_u64 v[220:221], s[46:47], 0, v[132:133]
	s_mov_b32 m0, s38
	s_nop 0
	global_load_lds_dwordx4 v[220:221], off
	s_waitcnt vmcnt(8)
	s_waitcnt lgkmcnt(0)
	s_barrier
	s_setprio 1
	s_waitcnt lgkmcnt(0)
	v_mfma_f32_16x16x32_bf16 v[126:129], v[144:147], v[176:179], v[126:129]
	v_mfma_f32_16x16x32_bf16 v[122:125], v[152:155], v[176:179], v[122:125]
	v_mfma_f32_16x16x32_bf16 v[118:121], v[144:147], v[184:187], v[118:121]
	v_mfma_f32_16x16x32_bf16 v[114:117], v[152:155], v[184:187], v[114:117]
	v_mfma_f32_16x16x32_bf16 v[102:105], v[144:147], v[198:201], v[102:105]
	v_mfma_f32_16x16x32_bf16 v[98:101], v[152:155], v[198:201], v[98:101]
	v_mfma_f32_16x16x32_bf16 v[86:89], v[144:147], v[206:209], v[86:89]
	v_mfma_f32_16x16x32_bf16 v[82:85], v[152:155], v[206:209], v[82:85]
	v_mfma_f32_16x16x32_bf16 v[126:129], v[148:151], v[180:183], v[126:129]
	v_mfma_f32_16x16x32_bf16 v[122:125], v[156:159], v[180:183], v[122:125]
	v_mfma_f32_16x16x32_bf16 v[118:121], v[148:151], v[188:191], v[118:121]
	v_mfma_f32_16x16x32_bf16 v[114:117], v[156:159], v[188:191], v[114:117]
	v_mfma_f32_16x16x32_bf16 v[102:105], v[148:151], v[202:205], v[102:105]
	v_mfma_f32_16x16x32_bf16 v[98:101], v[156:159], v[202:205], v[98:101]
	v_mfma_f32_16x16x32_bf16 v[86:89], v[148:151], v[210:213], v[86:89]
	v_mfma_f32_16x16x32_bf16 v[82:85], v[156:159], v[210:213], v[82:85]
	s_setprio 0
	s_setprio 1
	v_mfma_f32_16x16x32_bf16 v[110:113], v[160:163], v[176:179], v[110:113]
	v_mfma_f32_16x16x32_bf16 v[106:109], v[168:171], v[176:179], v[106:109]
	v_mfma_f32_16x16x32_bf16 v[94:97], v[160:163], v[184:187], v[94:97]
	v_mfma_f32_16x16x32_bf16 v[90:93], v[168:171], v[184:187], v[90:93]
	v_mfma_f32_16x16x32_bf16 v[78:81], v[160:163], v[198:201], v[78:81]
	v_mfma_f32_16x16x32_bf16 v[74:77], v[168:171], v[198:201], v[74:77]
	v_mfma_f32_16x16x32_bf16 v[70:73], v[160:163], v[206:209], v[70:73]
	v_mfma_f32_16x16x32_bf16 v[66:69], v[168:171], v[206:209], v[66:69]
	v_mfma_f32_16x16x32_bf16 v[110:113], v[164:167], v[180:183], v[110:113]
	v_mfma_f32_16x16x32_bf16 v[106:109], v[172:175], v[180:183], v[106:109]
	v_mfma_f32_16x16x32_bf16 v[94:97], v[164:167], v[188:191], v[94:97]
	v_mfma_f32_16x16x32_bf16 v[90:93], v[172:175], v[188:191], v[90:93]
	v_mfma_f32_16x16x32_bf16 v[78:81], v[164:167], v[202:205], v[78:81]
	v_mfma_f32_16x16x32_bf16 v[74:77], v[172:175], v[202:205], v[74:77]
	v_mfma_f32_16x16x32_bf16 v[70:73], v[164:167], v[210:213], v[70:73]
	v_mfma_f32_16x16x32_bf16 v[66:69], v[172:175], v[210:213], v[66:69]
	s_setprio 0
	s_barrier
; #define PG8_STAGE(bufoff, gbase, voff) do { _Pragma("unroll") for (int _i = 0; _i < 2; ++_i) \
;         __builtin_amdgcn_global_load_lds((const unsigned*)((const char*)(gbase) + (voff)[_i]), (PG8_LAS unsigned*)(lds + (bufoff) + ldsw + _i * 8192), 16, 0, 0); } while (0)
; #define PG8_LDA(dst, b, h) do { _Pragma("unroll") for (int m = 0; m < 4; ++m) _Pragma("unroll") for (int k = 0; k < 2; ++k) dst[m][k] = *(const PG8_LAS bf16x8*)(lds + PG8_SA(b, h) + aoff + m * 2048 + k * 1024); } while (0)
; #define PG8_LDB(dst, b, h) do { _Pragma("unroll") for (int n = 0; n < 2; ++n) _Pragma("unroll") for (int k = 0; k < 2; ++k) dst[n][k] = *(const PG8_LAS bf16x8*)(lds + PG8_SB(b, h) + boff + n * 2048 + k * 1024); } while (0)
; #define PG8_MMA(ai, bj, At, Bt) do { __builtin_amdgcn_s_setprio(1); _Pragma("unroll") for (int m = 0; m < 4; ++m) _Pragma("unroll") for (int n = 0; n < 2; ++n) _Pragma("unroll") for (int k = 0; k < 2; ++k) \
;         acc[ai][bj][m][n] = __builtin_amdgcn_mfma_f32_16x16x32_bf16(Bt[n][k], At[m][k], acc[ai][bj][m][n], 0, 0, 0); __builtin_amdgcn_s_setprio(0); } while (0)
; template <class Epi, class Sched, bool ALIGN_EPI = false, bool SP2 = false, bool KHOOK = false>
; __device__ __forceinline__ void gemm_phase(PG8_LAS unsigned char* lds, const Gemm g, const Sched& S, const Epi& E, const int tid_in) {
;     ...
;             PG8_LDB(B0, 0, 0); PG8_LDB(B1, 0, 1); PG8_SCHED; PG8_LDA(At, 0, 0); PG8_STAGE(PG8_SA(1, 1), a1 + hstep, voffA);
;             PG8_WAIT_V(8); PG8_WAIT_L(0); PG8_BAR; PG8_MMA(0, 0, At, B0); PG8_MMA(0, 1, At, B1); PG8_BAR; PG8_SCHED;
;             PG8_LDA(At, 0, 1); PG8_STAGE(PG8_SB(0, 0), b2, voffB); PG8_STAGE(PG8_SB(0, 1), b2 + hstep, voffB); PG8_STAGE(PG8_SA(0, 0), a2, voffA);
;             PG8_WAIT_V(8); PG8_WAIT_L(0); PG8_BAR; PG8_MMA(1, 0, At, B0); PG8_MMA(1, 1, At, B1); PG8_BAR; PG8_SCHED;
;             PG8_LDB(B0, 1, 0); PG8_LDB(B1, 1, 1); PG8_SCHED; PG8_LDA(At, 1, 0); PG8_STAGE(PG8_SA(0, 1), a2 + hstep, voffA);
;             PG8_WAIT_V(8); PG8_WAIT_L(0); PG8_BAR; PG8_MMA(0, 0, At, B0); PG8_MMA(0, 1, At, B1); PG8_BAR; PG8_SCHED;
;             PG8_LDA(At, 1, 1); PG8_STAGE(PG8_SB(1, 0), b3, voffB); PG8_STAGE(PG8_SB(1, 1), b3 + hstep, voffB); PG8_STAGE(PG8_SA(1, 0), a3, voffA);
;             PG8_WAIT_V(8); PG8_WAIT_L(0); PG8_BAR; PG8_MMA(1, 0, At, B0); PG8_MMA(1, 1, At, B1); PG8_BAR; PG8_SCHED;
	s_add_i32 s45, s45, s37
	v_lshl_add_u64 v[192:193], v[192:193], 0, s[90:91]
	s_mov_b32 m0, s45
	ds_read_b128 v[176:179], v143 offset:49152
	ds_read_b128 v[180:183], v143 offset:50176
	ds_read_b128 v[184:187], v143 offset:51200
	ds_read_b128 v[188:191], v143 offset:52224
	ds_read_b128 v[198:201], v143 offset:53248
	ds_read_b128 v[202:205], v143 offset:54272
	ds_read_b128 v[206:209], v143 offset:55296
	ds_read_b128 v[210:213], v143 offset:56320
	global_load_lds_dwordx4 v[192:193], off
	s_add_i32 m0, s45, 0x2000
	s_add_u32 s46, s52, 0x80080
	v_lshl_add_u64 v[192:193], v[214:215], 0, s[90:91]
	s_addc_u32 s47, s53, 0
	s_add_i32 s45, s50, s37
	global_load_lds_dwordx4 v[192:193], off
	v_lshl_add_u64 v[192:193], s[46:47], 0, v[32:33]
	s_mov_b32 m0, s45
	s_nop 0
	global_load_lds_dwordx4 v[192:193], off
	v_lshl_add_u64 v[192:193], s[46:47], 0, v[134:135]
	s_add_i32 m0, s45, 0x2000
	s_nop 0
	global_load_lds_dwordx4 v[192:193], off
	v_lshl_add_u64 v[192:193], v[216:217], 0, s[90:91]
	s_mov_b32 m0, s39
	s_nop 0
	global_load_lds_dwordx4 v[192:193], off
	v_lshl_add_u64 v[192:193], v[218:219], 0, s[90:91]
	s_mov_b32 m0, s40
	s_nop 0
	global_load_lds_dwordx4 v[192:193], off
	s_waitcnt vmcnt(8)
	s_waitcnt lgkmcnt(0)
	s_barrier
	s_setprio 1
	s_waitcnt lgkmcnt(0)
	v_mfma_f32_16x16x32_bf16 v[62:65], v[144:147], v[176:179], v[62:65]
	v_mfma_f32_16x16x32_bf16 v[58:61], v[152:155], v[176:179], v[58:61]
	v_mfma_f32_16x16x32_bf16 v[54:57], v[144:147], v[184:187], v[54:57]
	v_mfma_f32_16x16x32_bf16 v[50:53], v[152:155], v[184:187], v[50:53]
	v_mfma_f32_16x16x32_bf16 v[38:41], v[144:147], v[198:201], v[38:41]
	v_mfma_f32_16x16x32_bf16 v[34:37], v[152:155], v[198:201], v[34:37]
	v_mfma_f32_16x16x32_bf16 v[20:23], v[144:147], v[206:209], v[20:23]
	v_mfma_f32_16x16x32_bf16 v[16:19], v[152:155], v[206:209], v[16:19]
	v_mfma_f32_16x16x32_bf16 v[62:65], v[148:151], v[180:183], v[62:65]
	v_mfma_f32_16x16x32_bf16 v[58:61], v[156:159], v[180:183], v[58:61]
	v_mfma_f32_16x16x32_bf16 v[54:57], v[148:151], v[188:191], v[54:57]
	v_mfma_f32_16x16x32_bf16 v[50:53], v[156:159], v[188:191], v[50:53]
	v_mfma_f32_16x16x32_bf16 v[38:41], v[148:151], v[202:205], v[38:41]
	v_mfma_f32_16x16x32_bf16 v[34:37], v[156:159], v[202:205], v[34:37]
	v_mfma_f32_16x16x32_bf16 v[20:23], v[148:151], v[210:213], v[20:23]
	v_mfma_f32_16x16x32_bf16 v[16:19], v[156:159], v[210:213], v[16:19]
	s_setprio 0
	s_setprio 1
	v_mfma_f32_16x16x32_bf16 v[46:49], v[160:163], v[176:179], v[46:49]
	v_mfma_f32_16x16x32_bf16 v[42:45], v[168:171], v[176:179], v[42:45]
	v_mfma_f32_16x16x32_bf16 v[28:31], v[160:163], v[184:187], v[28:31]
	v_mfma_f32_16x16x32_bf16 v[24:27], v[168:171], v[184:187], v[24:27]
	v_mfma_f32_16x16x32_bf16 v[12:15], v[160:163], v[198:201], v[12:15]
	v_mfma_f32_16x16x32_bf16 v[8:11], v[168:171], v[198:201], v[8:11]
	v_mfma_f32_16x16x32_bf16 v[4:7], v[160:163], v[206:209], v[4:7]
	v_mfma_f32_16x16x32_bf16 v[0:3], v[168:171], v[206:209], v[0:3]
	v_mfma_f32_16x16x32_bf16 v[46:49], v[164:167], v[180:183], v[46:49]
	v_mfma_f32_16x16x32_bf16 v[42:45], v[172:175], v[180:183], v[42:45]
	v_mfma_f32_16x16x32_bf16 v[28:31], v[164:167], v[188:191], v[28:31]
	v_mfma_f32_16x16x32_bf16 v[24:27], v[172:175], v[188:191], v[24:27]
	v_mfma_f32_16x16x32_bf16 v[12:15], v[164:167], v[202:205], v[12:15]
	v_mfma_f32_16x16x32_bf16 v[8:11], v[172:175], v[202:205], v[8:11]
	v_mfma_f32_16x16x32_bf16 v[4:7], v[164:167], v[210:213], v[4:7]
	v_mfma_f32_16x16x32_bf16 v[0:3], v[172:175], v[210:213], v[0:3]
	s_setprio 0
	s_barrier
	s_add_i32 s44, s44, 2
	s_add_u32 s48, s48, 0x100
	s_addc_u32 s49, s49, 0
	s_add_u32 s19, s19, 0x100
	s_addc_u32 s42, s42, 0
	s_cmp_gt_u32 s44, 29
	s_branch .LBB0_263
.Lg1_peel_h:
	s_add_u32 s45, s48, 0xfff80080
	s_addc_u32 s46, s49, -1
	s_add_i32 s47, 0, 0x10000
	s_cmp_eq_u32 s44, 28
	s_cselect_b32 s57, s11, s46
	s_cselect_b32 s56, s17, s45
	s_cselect_b32 s53, s15, s42
	s_cselect_b32 s52, s18, s19
	s_add_i32 s45, 0, 0x14000
	v_add_u32_e32 v156, s47, v141
	v_add_u32_e32 v172, s45, v141
	ds_read_b128 v[144:147], v156
	ds_read_b128 v[148:151], v156 offset:1024
	ds_read_b128 v[152:155], v156 offset:2048
	ds_read_b128 v[156:159], v156 offset:3072
	ds_read_b128 v[160:163], v172
	ds_read_b128 v[164:167], v172 offset:1024
	ds_read_b128 v[168:171], v172 offset:2048
	ds_read_b128 v[172:175], v172 offset:3072
	ds_read_b128 v[176:179], v143
	ds_read_b128 v[180:183], v143 offset:1024
	ds_read_b128 v[184:187], v143 offset:2048
	ds_read_b128 v[188:191], v143 offset:3072
	ds_read_b128 v[198:201], v143 offset:4096
	ds_read_b128 v[202:205], v143 offset:5120
	ds_read_b128 v[206:209], v143 offset:6144
	ds_read_b128 v[210:213], v143 offset:7168
	s_waitcnt vmcnt(18)
	s_waitcnt lgkmcnt(0)
	s_barrier
; #define PG8_STAGE(bufoff, gbase, voff) do { _Pragma("unroll") for (int _i = 0; _i < 2; ++_i) \
;         __builtin_amdgcn_global_load_lds((const unsigned*)((const char*)(gbase) + (voff)[_i]), (PG8_LAS unsigned*)(lds + (bufoff) + ldsw + _i * 8192), 16, 0, 0); } while (0)
; #define PG8_LDA(dst, b, h) do { _Pragma("unroll") for (int m = 0; m < 4; ++m) _Pragma("unroll") for (int k = 0; k < 2; ++k) dst[m][k] = *(const PG8_LAS bf16x8*)(lds + PG8_SA(b, h) + aoff + m * 2048 + k * 1024); } while (0)
; #define PG8_LDB(dst, b, h) do { _Pragma("unroll") for (int n = 0; n < 2; ++n) _Pragma("unroll") for (int k = 0; k < 2; ++k) dst[n][k] = *(const PG8_LAS bf16x8*)(lds + PG8_SB(b, h) + boff + n * 2048 + k * 1024); } while (0)
; #define PG8_MMA(ai, bj, At, Bt) do { __builtin_amdgcn_s_setprio(1); _Pragma("unroll") for (int m = 0; m < 4; ++m) _Pragma("unroll") for (int n = 0; n < 2; ++n) _Pragma("unroll") for (int k = 0; k < 2; ++k) \
;         acc[ai][bj][m][n] = __builtin_amdgcn_mfma_f32_16x16x32_bf16(Bt[n][k], At[m][k], acc[ai][bj][m][n], 0, 0, 0); __builtin_amdgcn_s_setprio(0); } while (0)
; #define PG8_WAIT_V(n) asm volatile("s_waitcnt vmcnt(" #n ")" ::: "memory")
; #define PG8_WAIT_L(n) asm volatile("s_waitcnt lgkmcnt(" #n ")" ::: "memory")
; #define PG8_BAR __builtin_amdgcn_s_barrier()
; #define PG8_SCHED __builtin_amdgcn_sched_barrier(0)
; template <class Epi, class Sched, bool ALIGN_EPI = false, bool SP2 = false, bool KHOOK = false>
; __device__ __forceinline__ void gemm_phase(PG8_LAS unsigned char* lds, const Gemm g, const Sched& S, const Epi& E, const int tid_in) {
;     ...
;             PG8_WAIT_V(8); PG8_WAIT_L(0); PG8_BAR; PG8_MMA(0, 0, At, B0); PG8_MMA(0, 1, At, B1); PG8_BAR; PG8_SCHED;
;             PG8_LDA(At, 0, 1); PG8_STAGE(PG8_SB(0, 0), b2, voffB); PG8_STAGE(PG8_SB(0, 1), b2 + hstep, voffB); PG8_STAGE(PG8_SA(0, 0), a2, voffA);
;             PG8_WAIT_V(8); PG8_WAIT_L(0); PG8_BAR; PG8_MMA(1, 0, At, B0); PG8_MMA(1, 1, At, B1); PG8_BAR; PG8_SCHED;
;             PG8_LDB(B0, 1, 0); PG8_LDB(B1, 1, 1); PG8_SCHED; PG8_LDA(At, 1, 0); PG8_STAGE(PG8_SA(0, 1), a2 + hstep, voffA);
;             PG8_WAIT_V(8); PG8_WAIT_L(0); PG8_BAR; PG8_MMA(0, 0, At, B0); PG8_MMA(0, 1, At, B1); PG8_BAR; PG8_SCHED;
	s_setprio 1
	s_waitcnt lgkmcnt(0)
	v_mfma_f32_16x16x32_bf16 v[126:129], v[144:147], v[176:179], 0
	v_mfma_f32_16x16x32_bf16 v[122:125], v[152:155], v[176:179], 0
	v_mfma_f32_16x16x32_bf16 v[118:121], v[144:147], v[184:187], 0
	v_mfma_f32_16x16x32_bf16 v[114:117], v[152:155], v[184:187], 0
	v_mfma_f32_16x16x32_bf16 v[102:105], v[144:147], v[198:201], 0
	v_mfma_f32_16x16x32_bf16 v[98:101], v[152:155], v[198:201], 0
	v_mfma_f32_16x16x32_bf16 v[86:89], v[144:147], v[206:209], 0
	v_mfma_f32_16x16x32_bf16 v[82:85], v[152:155], v[206:209], 0
	v_mfma_f32_16x16x32_bf16 v[126:129], v[148:151], v[180:183], v[126:129]
	v_mfma_f32_16x16x32_bf16 v[122:125], v[156:159], v[180:183], v[122:125]
	v_mfma_f32_16x16x32_bf16 v[118:121], v[148:151], v[188:191], v[118:121]
	v_mfma_f32_16x16x32_bf16 v[114:117], v[156:159], v[188:191], v[114:117]
	v_mfma_f32_16x16x32_bf16 v[102:105], v[148:151], v[202:205], v[102:105]
	v_mfma_f32_16x16x32_bf16 v[98:101], v[156:159], v[202:205], v[98:101]
	v_mfma_f32_16x16x32_bf16 v[86:89], v[148:151], v[210:213], v[86:89]
	v_mfma_f32_16x16x32_bf16 v[82:85], v[156:159], v[210:213], v[82:85]
	s_setprio 0
	s_setprio 1
	v_mfma_f32_16x16x32_bf16 v[110:113], v[160:163], v[176:179], 0
	v_mfma_f32_16x16x32_bf16 v[106:109], v[168:171], v[176:179], 0
	v_mfma_f32_16x16x32_bf16 v[94:97], v[160:163], v[184:187], 0
	v_mfma_f32_16x16x32_bf16 v[90:93], v[168:171], v[184:187], 0
	v_mfma_f32_16x16x32_bf16 v[78:81], v[160:163], v[198:201], 0
	v_mfma_f32_16x16x32_bf16 v[74:77], v[168:171], v[198:201], 0
	v_mfma_f32_16x16x32_bf16 v[70:73], v[160:163], v[206:209], 0
	v_mfma_f32_16x16x32_bf16 v[66:69], v[168:171], v[206:209], 0
	v_mfma_f32_16x16x32_bf16 v[110:113], v[164:167], v[180:183], v[110:113]
	v_mfma_f32_16x16x32_bf16 v[106:109], v[172:175], v[180:183], v[106:109]
	v_mfma_f32_16x16x32_bf16 v[94:97], v[164:167], v[188:191], v[94:97]
	v_mfma_f32_16x16x32_bf16 v[90:93], v[172:175], v[188:191], v[90:93]
	v_mfma_f32_16x16x32_bf16 v[78:81], v[164:167], v[202:205], v[78:81]
	v_mfma_f32_16x16x32_bf16 v[74:77], v[172:175], v[202:205], v[74:77]
	v_mfma_f32_16x16x32_bf16 v[70:73], v[164:167], v[210:213], v[70:73]
	v_mfma_f32_16x16x32_bf16 v[66:69], v[172:175], v[210:213], v[66:69]
	s_setprio 0
	s_barrier
	s_add_i32 s46, s47, s37
	v_lshl_add_u64 v[192:193], s[52:53], 0, v[32:33]
	s_mov_b32 m0, s46
	ds_read_b128 v[176:179], v143 offset:16384
	ds_read_b128 v[180:183], v143 offset:17408
	ds_read_b128 v[184:187], v143 offset:18432
	ds_read_b128 v[188:191], v143 offset:19456
	ds_read_b128 v[198:201], v143 offset:20480
	ds_read_b128 v[202:205], v143 offset:21504
	ds_read_b128 v[206:209], v143 offset:22528
	ds_read_b128 v[210:213], v143 offset:23552
	global_load_lds_dwordx4 v[192:193], off
	s_add_i32 m0, s46, 0x2000
	s_add_u32 s46, s52, 0x80000
	v_lshl_add_u64 v[214:215], s[52:53], 0, v[134:135]
	s_addc_u32 s47, s53, 0
	s_add_i32 s45, s45, s37
	global_load_lds_dwordx4 v[214:215], off
	v_lshl_add_u64 v[216:217], s[46:47], 0, v[32:33]
	s_mov_b32 m0, s45
	v_lshl_add_u64 v[218:219], s[56:57], 0, v[132:133]
	global_load_lds_dwordx4 v[216:217], off
	v_lshl_add_u64 v[216:217], s[46:47], 0, v[134:135]
	s_add_i32 m0, s45, 0x2000
	s_nop 0
	global_load_lds_dwordx4 v[216:217], off
	v_lshl_add_u64 v[216:217], s[56:57], 0, v[130:131]
	s_mov_b32 m0, s13
	s_nop 0
	global_load_lds_dwordx4 v[216:217], off
	s_mov_b32 m0, s24
	s_nop 0
	global_load_lds_dwordx4 v[218:219], off
	s_waitcnt vmcnt(24)
	s_waitcnt lgkmcnt(0)
	s_barrier
	s_setprio 1
	s_waitcnt lgkmcnt(0)
	v_mfma_f32_16x16x32_bf16 v[62:65], v[144:147], v[176:179], 0
	v_mfma_f32_16x16x32_bf16 v[58:61], v[152:155], v[176:179], 0
	v_mfma_f32_16x16x32_bf16 v[54:57], v[144:147], v[184:187], 0
	v_mfma_f32_16x16x32_bf16 v[50:53], v[152:155], v[184:187], 0
	v_mfma_f32_16x16x32_bf16 v[38:41], v[144:147], v[198:201], 0
	v_mfma_f32_16x16x32_bf16 v[34:37], v[152:155], v[198:201], 0
	v_mfma_f32_16x16x32_bf16 v[20:23], v[144:147], v[206:209], 0
	v_mfma_f32_16x16x32_bf16 v[16:19], v[152:155], v[206:209], 0
	v_mfma_f32_16x16x32_bf16 v[62:65], v[148:151], v[180:183], v[62:65]
	v_mfma_f32_16x16x32_bf16 v[58:61], v[156:159], v[180:183], v[58:61]
	v_mfma_f32_16x16x32_bf16 v[54:57], v[148:151], v[188:191], v[54:57]
	v_mfma_f32_16x16x32_bf16 v[50:53], v[156:159], v[188:191], v[50:53]
	v_mfma_f32_16x16x32_bf16 v[38:41], v[148:151], v[202:205], v[38:41]
	v_mfma_f32_16x16x32_bf16 v[34:37], v[156:159], v[202:205], v[34:37]
	v_mfma_f32_16x16x32_bf16 v[20:23], v[148:151], v[210:213], v[20:23]
	v_mfma_f32_16x16x32_bf16 v[16:19], v[156:159], v[210:213], v[16:19]
	s_setprio 0
	s_setprio 1
	v_mfma_f32_16x16x32_bf16 v[46:49], v[160:163], v[176:179], 0
	v_mfma_f32_16x16x32_bf16 v[42:45], v[168:171], v[176:179], 0
	v_mfma_f32_16x16x32_bf16 v[28:31], v[160:163], v[184:187], 0
	v_mfma_f32_16x16x32_bf16 v[24:27], v[168:171], v[184:187], 0
	v_mfma_f32_16x16x32_bf16 v[12:15], v[160:163], v[198:201], 0
	v_mfma_f32_16x16x32_bf16 v[8:11], v[168:171], v[198:201], 0
	v_mfma_f32_16x16x32_bf16 v[4:7], v[160:163], v[206:209], 0
	v_mfma_f32_16x16x32_bf16 v[0:3], v[168:171], v[206:209], 0
	v_mfma_f32_16x16x32_bf16 v[46:49], v[164:167], v[180:183], v[46:49]
	v_mfma_f32_16x16x32_bf16 v[42:45], v[172:175], v[180:183], v[42:45]
	v_mfma_f32_16x16x32_bf16 v[28:31], v[164:167], v[188:191], v[28:31]
	v_mfma_f32_16x16x32_bf16 v[24:27], v[172:175], v[188:191], v[24:27]
	v_mfma_f32_16x16x32_bf16 v[12:15], v[164:167], v[202:205], v[12:15]
	v_mfma_f32_16x16x32_bf16 v[8:11], v[172:175], v[202:205], v[8:11]
	v_mfma_f32_16x16x32_bf16 v[4:7], v[164:167], v[210:213], v[4:7]
	v_mfma_f32_16x16x32_bf16 v[0:3], v[172:175], v[210:213], v[0:3]
	s_setprio 0
	s_barrier
; #define PG8_STAGE(bufoff, gbase, voff) do { _Pragma("unroll") for (int _i = 0; _i < 2; ++_i) \
;         __builtin_amdgcn_global_load_lds((const unsigned*)((const char*)(gbase) + (voff)[_i]), (PG8_LAS unsigned*)(lds + (bufoff) + ldsw + _i * 8192), 16, 0, 0); } while (0)
; #define PG8_LDA(dst, b, h) do { _Pragma("unroll") for (int m = 0; m < 4; ++m) _Pragma("unroll") for (int k = 0; k < 2; ++k) dst[m][k] = *(const PG8_LAS bf16x8*)(lds + PG8_SA(b, h) + aoff + m * 2048 + k * 1024); } while (0)
; #define PG8_LDB(dst, b, h) do { _Pragma("unroll") for (int n = 0; n < 2; ++n) _Pragma("unroll") for (int k = 0; k < 2; ++k) dst[n][k] = *(const PG8_LAS bf16x8*)(lds + PG8_SB(b, h) + boff + n * 2048 + k * 1024); } while (0)
; #define PG8_MMA(ai, bj, At, Bt) do { __builtin_amdgcn_s_setprio(1); _Pragma("unroll") for (int m = 0; m < 4; ++m) _Pragma("unroll") for (int n = 0; n < 2; ++n) _Pragma("unroll") for (int k = 0; k < 2; ++k) \
;         acc[ai][bj][m][n] = __builtin_amdgcn_mfma_f32_16x16x32_bf16(Bt[n][k], At[m][k], acc[ai][bj][m][n], 0, 0, 0); __builtin_amdgcn_s_setprio(0); } while (0)
; #define PG8_WAIT_V(n) asm volatile("s_waitcnt vmcnt(" #n ")" ::: "memory")
; #define PG8_WAIT_L(n) asm volatile("s_waitcnt lgkmcnt(" #n ")" ::: "memory")
; #define PG8_BAR __builtin_amdgcn_s_barrier()
; #define PG8_SCHED __builtin_amdgcn_sched_barrier(0)
; template <class Epi, class Sched, bool ALIGN_EPI = false, bool SP2 = false, bool KHOOK = false>
; __device__ __forceinline__ void gemm_phase(PG8_LAS unsigned char* lds, const Gemm g, const Sched& S, const Epi& E, const int tid_in) {
;     ...
;             PG8_LDB(B0, 1, 0); PG8_LDB(B1, 1, 1); PG8_SCHED; PG8_LDA(At, 1, 0); PG8_STAGE(PG8_SA(0, 1), a2 + hstep, voffA);
;             PG8_WAIT_V(8); PG8_WAIT_L(0); PG8_BAR; PG8_MMA(0, 0, At, B0); PG8_MMA(0, 1, At, B1); PG8_BAR; PG8_SCHED;
	s_add_i32 s45, 0, 0x18000
	s_add_i32 s50, 0, 0x1c000
	v_add_u32_e32 v156, s45, v141
	v_add_u32_e32 v172, s50, v141
	ds_read_b128 v[144:147], v156
	ds_read_b128 v[148:151], v156 offset:1024
	ds_read_b128 v[152:155], v156 offset:2048
	ds_read_b128 v[156:159], v156 offset:3072
	ds_read_b128 v[160:163], v172
	ds_read_b128 v[164:167], v172 offset:1024
	ds_read_b128 v[168:171], v172 offset:2048
	ds_read_b128 v[172:175], v172 offset:3072
	s_add_u32 s46, s56, 0x80000
	s_addc_u32 s47, s57, 0
	s_mov_b32 m0, s25
	v_lshl_add_u64 v[220:221], s[46:47], 0, v[130:131]
	ds_read_b128 v[176:179], v143 offset:32768
	ds_read_b128 v[180:183], v143 offset:33792
	ds_read_b128 v[184:187], v143 offset:34816
	ds_read_b128 v[188:191], v143 offset:35840
	ds_read_b128 v[198:201], v143 offset:36864
	ds_read_b128 v[202:205], v143 offset:37888
	ds_read_b128 v[206:209], v143 offset:38912
	ds_read_b128 v[210:213], v143 offset:39936
	global_load_lds_dwordx4 v[220:221], off
	v_lshl_add_u64 v[220:221], s[46:47], 0, v[132:133]
	s_mov_b32 m0, s38
	s_nop 0
	global_load_lds_dwordx4 v[220:221], off
	s_waitcnt vmcnt(24)
	s_waitcnt lgkmcnt(0)
	s_barrier
	s_setprio 1
	s_waitcnt lgkmcnt(0)
	v_mfma_f32_16x16x32_bf16 v[126:129], v[144:147], v[176:179], v[126:129]
	v_mfma_f32_16x16x32_bf16 v[122:125], v[152:155], v[176:179], v[122:125]
	v_mfma_f32_16x16x32_bf16 v[118:121], v[144:147], v[184:187], v[118:121]
	v_mfma_f32_16x16x32_bf16 v[114:117], v[152:155], v[184:187], v[114:117]
	v_mfma_f32_16x16x32_bf16 v[102:105], v[144:147], v[198:201], v[102:105]
	v_mfma_f32_16x16x32_bf16 v[98:101], v[152:155], v[198:201], v[98:101]
	v_mfma_f32_16x16x32_bf16 v[86:89], v[144:147], v[206:209], v[86:89]
	v_mfma_f32_16x16x32_bf16 v[82:85], v[152:155], v[206:209], v[82:85]
	v_mfma_f32_16x16x32_bf16 v[126:129], v[148:151], v[180:183], v[126:129]
	v_mfma_f32_16x16x32_bf16 v[122:125], v[156:159], v[180:183], v[122:125]
	v_mfma_f32_16x16x32_bf16 v[118:121], v[148:151], v[188:191], v[118:121]
	v_mfma_f32_16x16x32_bf16 v[114:117], v[156:159], v[188:191], v[114:117]
	v_mfma_f32_16x16x32_bf16 v[102:105], v[148:151], v[202:205], v[102:105]
	v_mfma_f32_16x16x32_bf16 v[98:101], v[156:159], v[202:205], v[98:101]
	v_mfma_f32_16x16x32_bf16 v[86:89], v[148:151], v[210:213], v[86:89]
	v_mfma_f32_16x16x32_bf16 v[82:85], v[156:159], v[210:213], v[82:85]
	s_setprio 0
	s_setprio 1
	v_mfma_f32_16x16x32_bf16 v[110:113], v[160:163], v[176:179], v[110:113]
	v_mfma_f32_16x16x32_bf16 v[106:109], v[168:171], v[176:179], v[106:109]
	v_mfma_f32_16x16x32_bf16 v[94:97], v[160:163], v[184:187], v[94:97]
	v_mfma_f32_16x16x32_bf16 v[90:93], v[168:171], v[184:187], v[90:93]
	v_mfma_f32_16x16x32_bf16 v[78:81], v[160:163], v[198:201], v[78:81]
	v_mfma_f32_16x16x32_bf16 v[74:77], v[168:171], v[198:201], v[74:77]
	v_mfma_f32_16x16x32_bf16 v[70:73], v[160:163], v[206:209], v[70:73]
	v_mfma_f32_16x16x32_bf16 v[66:69], v[168:171], v[206:209], v[66:69]
	v_mfma_f32_16x16x32_bf16 v[110:113], v[164:167], v[180:183], v[110:113]
	v_mfma_f32_16x16x32_bf16 v[106:109], v[172:175], v[180:183], v[106:109]
	v_mfma_f32_16x16x32_bf16 v[94:97], v[164:167], v[188:191], v[94:97]
	v_mfma_f32_16x16x32_bf16 v[90:93], v[172:175], v[188:191], v[90:93]
	v_mfma_f32_16x16x32_bf16 v[78:81], v[164:167], v[202:205], v[78:81]
	v_mfma_f32_16x16x32_bf16 v[74:77], v[172:175], v[202:205], v[74:77]
	v_mfma_f32_16x16x32_bf16 v[70:73], v[164:167], v[210:213], v[70:73]
	v_mfma_f32_16x16x32_bf16 v[66:69], v[172:175], v[210:213], v[66:69]
	s_setprio 0
	s_barrier
; #define PG8_STAGE(bufoff, gbase, voff) do { _Pragma("unroll") for (int _i = 0; _i < 2; ++_i) \
;         __builtin_amdgcn_global_load_lds((const unsigned*)((const char*)(gbase) + (voff)[_i]), (PG8_LAS unsigned*)(lds + (bufoff) + ldsw + _i * 8192), 16, 0, 0); } while (0)
; #define PG8_LDA(dst, b, h) do { _Pragma("unroll") for (int m = 0; m < 4; ++m) _Pragma("unroll") for (int k = 0; k < 2; ++k) dst[m][k] = *(const PG8_LAS bf16x8*)(lds + PG8_SA(b, h) + aoff + m * 2048 + k * 1024); } while (0)
; #define PG8_MMA(ai, bj, At, Bt) do { __builtin_amdgcn_s_setprio(1); _Pragma("unroll") for (int m = 0; m < 4; ++m) _Pragma("unroll") for (int n = 0; n < 2; ++n) _Pragma("unroll") for (int k = 0; k < 2; ++k) \
;         acc[ai][bj][m][n] = __builtin_amdgcn_mfma_f32_16x16x32_bf16(Bt[n][k], At[m][k], acc[ai][bj][m][n], 0, 0, 0); __builtin_amdgcn_s_setprio(0); } while (0)
; #define PG8_WAIT_V(n) asm volatile("s_waitcnt vmcnt(" #n ")" ::: "memory")
; #define PG8_WAIT_L(n) asm volatile("s_waitcnt lgkmcnt(" #n ")" ::: "memory")
; #define PG8_BAR __builtin_amdgcn_s_barrier()
; #define PG8_SCHED __builtin_amdgcn_sched_barrier(0)
; template <class Epi, class Sched, bool ALIGN_EPI = false, bool SP2 = false, bool KHOOK = false>
; __device__ __forceinline__ void gemm_phase(PG8_LAS unsigned char* lds, const Gemm g, const Sched& S, const Epi& E, const int tid_in) {
;     ...
;         for (int t = 0; t < nt; t += 2) {
;     ...
;             PG8_LDA(At, 1, 1); PG8_STAGE(PG8_SB(1, 0), b3, voffB); PG8_STAGE(PG8_SB(1, 1), b3 + hstep, voffB); PG8_STAGE(PG8_SA(1, 0), a3, voffA);
;             PG8_WAIT_V(8); PG8_WAIT_L(0); PG8_BAR; PG8_MMA(1, 0, At, B0); PG8_MMA(1, 1, At, B1); PG8_BAR; PG8_SCHED;
	s_add_i32 s45, s45, s37
	v_lshl_add_u64 v[192:193], v[192:193], 0, s[90:91]
	s_mov_b32 m0, s45
	ds_read_b128 v[176:179], v143 offset:49152
	ds_read_b128 v[180:183], v143 offset:50176
	ds_read_b128 v[184:187], v143 offset:51200
	ds_read_b128 v[188:191], v143 offset:52224
	ds_read_b128 v[198:201], v143 offset:53248
	ds_read_b128 v[202:205], v143 offset:54272
	ds_read_b128 v[206:209], v143 offset:55296
	ds_read_b128 v[210:213], v143 offset:56320
	global_load_lds_dwordx4 v[192:193], off
	s_add_i32 m0, s45, 0x2000
	s_add_u32 s46, s52, 0x80080
	v_lshl_add_u64 v[192:193], v[214:215], 0, s[90:91]
	s_addc_u32 s47, s53, 0
	s_add_i32 s45, s50, s37
	global_load_lds_dwordx4 v[192:193], off
	v_lshl_add_u64 v[192:193], s[46:47], 0, v[32:33]
	s_mov_b32 m0, s45
	s_nop 0
	global_load_lds_dwordx4 v[192:193], off
	v_lshl_add_u64 v[192:193], s[46:47], 0, v[134:135]
	s_add_i32 m0, s45, 0x2000
	s_nop 0
	global_load_lds_dwordx4 v[192:193], off
	v_lshl_add_u64 v[192:193], v[216:217], 0, s[90:91]
	s_mov_b32 m0, s39
	s_nop 0
	global_load_lds_dwordx4 v[192:193], off
	v_lshl_add_u64 v[192:193], v[218:219], 0, s[90:91]
	s_mov_b32 m0, s40
	s_nop 0
	global_load_lds_dwordx4 v[192:193], off
	s_waitcnt vmcnt(8)
	s_waitcnt lgkmcnt(0)
	s_barrier
	s_setprio 1
	s_waitcnt lgkmcnt(0)
	v_mfma_f32_16x16x32_bf16 v[62:65], v[144:147], v[176:179], v[62:65]
	v_mfma_f32_16x16x32_bf16 v[58:61], v[152:155], v[176:179], v[58:61]
	v_mfma_f32_16x16x32_bf16 v[54:57], v[144:147], v[184:187], v[54:57]
	v_mfma_f32_16x16x32_bf16 v[50:53], v[152:155], v[184:187], v[50:53]
	v_mfma_f32_16x16x32_bf16 v[38:41], v[144:147], v[198:201], v[38:41]
	v_mfma_f32_16x16x32_bf16 v[34:37], v[152:155], v[198:201], v[34:37]
	v_mfma_f32_16x16x32_bf16 v[20:23], v[144:147], v[206:209], v[20:23]
	v_mfma_f32_16x16x32_bf16 v[16:19], v[152:155], v[206:209], v[16:19]
	v_mfma_f32_16x16x32_bf16 v[62:65], v[148:151], v[180:183], v[62:65]
	v_mfma_f32_16x16x32_bf16 v[58:61], v[156:159], v[180:183], v[58:61]
	v_mfma_f32_16x16x32_bf16 v[54:57], v[148:151], v[188:191], v[54:57]
	v_mfma_f32_16x16x32_bf16 v[50:53], v[156:159], v[188:191], v[50:53]
	v_mfma_f32_16x16x32_bf16 v[38:41], v[148:151], v[202:205], v[38:41]
	v_mfma_f32_16x16x32_bf16 v[34:37], v[156:159], v[202:205], v[34:37]
	v_mfma_f32_16x16x32_bf16 v[20:23], v[148:151], v[210:213], v[20:23]
	v_mfma_f32_16x16x32_bf16 v[16:19], v[156:159], v[210:213], v[16:19]
	s_setprio 0
	s_setprio 1
	v_mfma_f32_16x16x32_bf16 v[46:49], v[160:163], v[176:179], v[46:49]
	v_mfma_f32_16x16x32_bf16 v[42:45], v[168:171], v[176:179], v[42:45]
	v_mfma_f32_16x16x32_bf16 v[28:31], v[160:163], v[184:187], v[28:31]
	v_mfma_f32_16x16x32_bf16 v[24:27], v[168:171], v[184:187], v[24:27]
	v_mfma_f32_16x16x32_bf16 v[12:15], v[160:163], v[198:201], v[12:15]
	v_mfma_f32_16x16x32_bf16 v[8:11], v[168:171], v[198:201], v[8:11]
	v_mfma_f32_16x16x32_bf16 v[4:7], v[160:163], v[206:209], v[4:7]
	v_mfma_f32_16x16x32_bf16 v[0:3], v[168:171], v[206:209], v[0:3]
	v_mfma_f32_16x16x32_bf16 v[46:49], v[164:167], v[180:183], v[46:49]
	v_mfma_f32_16x16x32_bf16 v[42:45], v[172:175], v[180:183], v[42:45]
	v_mfma_f32_16x16x32_bf16 v[28:31], v[164:167], v[188:191], v[28:31]
	v_mfma_f32_16x16x32_bf16 v[24:27], v[172:175], v[188:191], v[24:27]
	v_mfma_f32_16x16x32_bf16 v[12:15], v[164:167], v[202:205], v[12:15]
	v_mfma_f32_16x16x32_bf16 v[8:11], v[172:175], v[202:205], v[8:11]
	v_mfma_f32_16x16x32_bf16 v[4:7], v[164:167], v[210:213], v[4:7]
	v_mfma_f32_16x16x32_bf16 v[0:3], v[172:175], v[210:213], v[0:3]
	s_setprio 0
	s_barrier
	s_add_i32 s44, s44, 2
	s_add_u32 s48, s48, 0x100
	s_addc_u32 s49, s49, 0
	s_add_u32 s19, s19, 0x100
	s_addc_u32 s42, s42, 0
	s_cmp_gt_u32 s44, 29

; __device__ __forceinline__ unsigned cvt_pk_bf16(float lo, float hi) { const f32x2_t v = {lo, hi}; const bf16x2_t c = __builtin_convertvector(v, bf16x2_t); return __builtin_bit_cast(unsigned, c); }
; #define PG8_BAR __builtin_amdgcn_s_barrier()
;     __device__ __forceinline__ void operator()(const f32x4 (&acc)[2][2][4][2], const Unit& u, int wr, int wc, int fr, int fq) const {
;         const int row0 = u.pm * BM + wr * 64 + fr, col0 = u.pn * BM + wc * 32 + 8 * fq;
; #pragma unroll
;         for (int ai = 0; ai < 2; ++ai)
; #pragma unroll
;             for (int m = 0; m < 4; ++m) { bf16_t* rowp = O + (size_t)(row0 + ai * HALF + m * 16) * ldc + col0;
; #pragma unroll
;                 for (int bj = 0; bj < 2; ++bj) { const f32x4 v0 = acc[ai][bj][m][0], v1 = acc[ai][bj][m][1];
;                     u32x4 w; w.x = cvt_pk_bf16(v0[0], v0[1]); w.y = cvt_pk_bf16(v0[2], v0[3]); w.z = cvt_pk_bf16(v1[0], v1[1]); w.w = cvt_pk_bf16(v1[2], v1[3]);
;                     *(u32x4*)(rowp + bj * HALF) = w; } }
; template <class Epi, class Sched, bool ALIGN_EPI = false, bool SP2 = false, bool KHOOK = false>
; __device__ __forceinline__ void gemm_phase(PG8_LAS unsigned char* lds, const Gemm g, const Sched& S, const Epi& E, const int tid_in) {
;     ...
;         if constexpr (!Epi::AFTER_DRAIN) { E(acc, cur, wr, wc, fr, fq); S.done(cur); }
;         if (!has_next) break;
; #pragma unroll
;         for (int a = 0; a < 2; ++a)
; #pragma unroll
;             for (int b = 0; b < 2; ++b)
; #pragma unroll
;                 for (int m = 0; m < 4; ++m)
; #pragma unroll
;                     for (int n = 0; n < 2; ++n) acc[a][b][m][n] = (f32x4){0.f, 0.f, 0.f, 0.f};
;         cur = nxt; cA = nA; cB = nB; ++ui; load_rr(cur);
;         if constexpr (ALIGN_EPI) { if (wr == 1) PG8_BAR; }
.LBB0_266:
	s_add_u32 s64, s17, 0x80080
	s_addc_u32 s65, s11, 0
	v_lshl_add_u64 v[192:193], s[64:65], 0, v[136:137]
	s_add_i32 m0, s13, 0xc000
	s_nop 0
	global_load_lds_dwordx4 v[192:193], off
	v_lshl_add_u64 v[192:193], s[64:65], 0, v[138:139]
	s_add_i32 m0, s13, 0xe000
	s_nop 0
	global_load_lds_dwordx4 v[192:193], off
	s_mov_b32 s60, 1
	v_lshl_add_u32 v150, s12, 8, v140
	v_lshl_or_b32 v144, s10, 8, v142
	v_ashrrev_i32_e32 v145, 31, v144
	v_mov_b64_e32 v[146:147], s[76:77]
	v_cvt_pk_bf16_f32 v70, v70, v71
	v_cvt_pk_bf16_f32 v71, v72, v73
	v_cvt_pk_bf16_f32 v72, v66, v67
	v_add_u32_e32 v66, 0x80, v150
	v_mad_i64_i32 v[148:149], s[10:11], v150, s67, v[146:147]
	v_lshlrev_b64 v[144:145], 1, v[144:145]
	v_cvt_pk_bf16_f32 v110, v110, v111
	v_cvt_pk_bf16_f32 v111, v112, v113
	v_cvt_pk_bf16_f32 v112, v106, v107
	v_or_b32_e32 v106, 16, v150
	v_mad_i64_i32 v[66:67], s[10:11], v66, s67, v[146:147]
	v_cvt_pk_bf16_f32 v46, v46, v47
	v_cvt_pk_bf16_f32 v47, v48, v49
	v_cvt_pk_bf16_f32 v48, v42, v43
	v_add_u32_e32 v42, 0x90, v150
	v_lshl_add_u64 v[148:149], v[148:149], 0, v[144:145]
	v_cvt_pk_bf16_f32 v113, v108, v109
	v_mad_i64_i32 v[106:107], s[10:11], v106, s67, v[146:147]
	v_cvt_pk_bf16_f32 v94, v94, v95
	v_cvt_pk_bf16_f32 v95, v96, v97
	v_cvt_pk_bf16_f32 v96, v90, v91
	v_or_b32_e32 v90, 32, v150
	v_lshl_add_u64 v[66:67], v[66:67], 0, v[144:145]
	v_cvt_pk_bf16_f32 v49, v44, v45
	v_mad_i64_i32 v[42:43], s[10:11], v42, s67, v[146:147]
	v_cvt_pk_bf16_f32 v28, v28, v29
	v_cvt_pk_bf16_f32 v29, v30, v31
	v_cvt_pk_bf16_f32 v30, v24, v25
	v_add_u32_e32 v24, 0xa0, v150
	global_store_dwordx4 v[148:149], v[110:113], off offset:256
	v_cvt_pk_bf16_f32 v97, v92, v93
	v_mad_i64_i32 v[90:91], s[10:11], v90, s67, v[146:147]
	v_lshl_add_u64 v[110:111], v[106:107], 0, v[144:145]
	v_cvt_pk_bf16_f32 v78, v78, v79
	v_cvt_pk_bf16_f32 v79, v80, v81
	v_cvt_pk_bf16_f32 v80, v74, v75
	v_or_b32_e32 v74, 48, v150
	global_store_dwordx4 v[66:67], v[46:49], off offset:256
	v_cvt_pk_bf16_f32 v31, v26, v27
	v_mad_i64_i32 v[24:25], s[10:11], v24, s67, v[146:147]
	v_lshl_add_u64 v[46:47], v[42:43], 0, v[144:145]
	v_cvt_pk_bf16_f32 v12, v12, v13
	v_cvt_pk_bf16_f32 v13, v14, v15
	v_cvt_pk_bf16_f32 v14, v8, v9
	v_add_u32_e32 v8, 0xb0, v150
	global_store_dwordx4 v[110:111], v[94:97], off offset:256
	v_cvt_pk_bf16_f32 v81, v76, v77
	v_mad_i64_i32 v[74:75], s[10:11], v74, s67, v[146:147]
	v_lshl_add_u64 v[94:95], v[90:91], 0, v[144:145]
	global_store_dwordx4 v[46:47], v[28:31], off offset:256
	v_cvt_pk_bf16_f32 v15, v10, v11
	v_mad_i64_i32 v[8:9], s[10:11], v8, s67, v[146:147]
	v_lshl_add_u64 v[28:29], v[24:25], 0, v[144:145]
	v_cvt_pk_bf16_f32 v126, v126, v127
	v_cvt_pk_bf16_f32 v127, v128, v129
	v_cvt_pk_bf16_f32 v128, v122, v123
	v_cvt_pk_bf16_f32 v129, v124, v125
	v_cvt_pk_bf16_f32 v106, v118, v119
	v_cvt_pk_bf16_f32 v107, v120, v121
	v_cvt_pk_bf16_f32 v108, v114, v115
	v_cvt_pk_bf16_f32 v109, v116, v117
	v_cvt_pk_bf16_f32 v90, v102, v103
	v_cvt_pk_bf16_f32 v91, v104, v105
	v_cvt_pk_bf16_f32 v92, v98, v99
	v_cvt_pk_bf16_f32 v93, v100, v101
	global_store_dwordx4 v[94:95], v[78:81], off offset:256
	v_cvt_pk_bf16_f32 v76, v82, v83
	v_cvt_pk_bf16_f32 v77, v84, v85
	v_lshl_add_u64 v[78:79], v[74:75], 0, v[144:145]
	v_cvt_pk_bf16_f32 v74, v86, v87
	v_cvt_pk_bf16_f32 v75, v88, v89
	v_cvt_pk_bf16_f32 v73, v68, v69
	v_cvt_pk_bf16_f32 v62, v62, v63
	v_cvt_pk_bf16_f32 v63, v64, v65
	v_cvt_pk_bf16_f32 v64, v58, v59
	v_cvt_pk_bf16_f32 v65, v60, v61
	v_cvt_pk_bf16_f32 v42, v54, v55
	v_cvt_pk_bf16_f32 v43, v56, v57
	v_cvt_pk_bf16_f32 v44, v50, v51
	v_cvt_pk_bf16_f32 v45, v52, v53
	v_cvt_pk_bf16_f32 v24, v38, v39
	v_cvt_pk_bf16_f32 v25, v40, v41
	v_cvt_pk_bf16_f32 v26, v34, v35
	v_cvt_pk_bf16_f32 v27, v36, v37
	global_store_dwordx4 v[28:29], v[12:15], off offset:256
	v_cvt_pk_bf16_f32 v10, v16, v17
	v_cvt_pk_bf16_f32 v11, v18, v19
	v_lshl_add_u64 v[12:13], v[8:9], 0, v[144:145]
	v_cvt_pk_bf16_f32 v8, v20, v21
	v_cvt_pk_bf16_f32 v9, v22, v23
	v_cvt_pk_bf16_f32 v4, v4, v5
	v_cvt_pk_bf16_f32 v5, v6, v7
	v_cvt_pk_bf16_f32 v6, v0, v1
	v_cvt_pk_bf16_f32 v7, v2, v3
	s_andn2_b64 vcc, exec, s[22:23]
	s_mov_b64 s[10:11], -1
	global_store_dwordx4 v[148:149], v[126:129], off
	global_store_dwordx4 v[110:111], v[106:109], off
	global_store_dwordx4 v[94:95], v[90:93], off
	global_store_dwordx4 v[78:79], v[74:77], off
	global_store_dwordx4 v[78:79], v[70:73], off offset:256
	global_store_dwordx4 v[66:67], v[62:65], off
	global_store_dwordx4 v[46:47], v[42:45], off
	global_store_dwordx4 v[28:29], v[24:27], off
	global_store_dwordx4 v[12:13], v[8:11], off
	global_store_dwordx4 v[12:13], v[4:7], off offset:256
	s_cbranch_vccnz .LBB0_258
	s_andn2_b64 vcc, exec, s[6:7]
	s_cbranch_vccnz .LBB0_257
	s_barrier
	s_branch .LBB0_257

; #define PG8_STAGE(bufoff, gbase, voff) do { _Pragma("unroll") for (int _i = 0; _i < 2; ++_i) \
;         __builtin_amdgcn_global_load_lds((const unsigned*)((const char*)(gbase) + (voff)[_i]), (PG8_LAS unsigned*)(lds + (bufoff) + ldsw + _i * 8192), 16, 0, 0); } while (0)
; #define PG8_WAIT_V(n) asm volatile("s_waitcnt vmcnt(" #n ")" ::: "memory")
; #define PG8_BAR __builtin_amdgcn_s_barrier()
; template <class Epi, class Sched, bool ALIGN_EPI = false, bool SP2 = false, bool KHOOK = false>
; __device__ __forceinline__ void gemm_phase(PG8_LAS unsigned char* lds, const Gemm g, const Sched& S, const Epi& E, const int tid_in) {
;     ...
;     for (int i = 0; i < 2; ++i) { int R, C; stage_rc(tid * 16 + i * 8192, R, C); const int Rb = Epi::PERM ? ((R & ~31) + perm32(R & 31)) : R;
;         voffA[i] = (unsigned)(R * LD + C) * 2u; voffB[i] = (unsigned)(Rb * LD + C) * 2u; }
;     const size_t kstep = (size_t)(BK * 2);
;     const size_t hstep = (size_t)HALF * LD * 2;
;     const size_t tstep = 2 * hstep;
;     const unsigned ldsw = (unsigned)wid * 1024u;
;     const int aoff = lds_byte(wr * 64 + fr, fq * 8), boff = lds_byte(wc * 32 + fr, fq * 8);
;     ...
;     if constexpr (SP2) {
;         PG8_STAGE(PG8_SB(0, 0), cB, voffB); PG8_STAGE(PG8_SB(0, 1), cB + hstep, voffB); PG8_STAGE(PG8_SA(0, 0), cA, voffA); PG8_STAGE(PG8_SA(0, 1), cA + hstep, voffA);
;         if (wr == 1) PG8_BAR;
;         PG8_WAIT_V(2); PG8_BAR;
;         PG8_STAGE(PG8_SB(1, 0), cB + kstep, voffB); PG8_STAGE(PG8_SA(1, 0), cA + kstep, voffA); PG8_STAGE(PG8_SB(1, 1), cB + hstep + kstep, voffB);
;         PG8_WAIT_V(6); PG8_BAR;
.LBB0_1056:
	v_lshrrev_b32_e32 v16, 1, v6
	v_and_b32_e32 v16, 24, v16
	s_lshl_b32 s5, s5, 5
	v_and_b32_e32 v7, 15, v6
	v_lshlrev_b32_e32 v17, 1, v16
	v_lshlrev_b32_e32 v6, 2, v6
	s_and_b32 s12, s5, 0x60
	v_lshl_add_u64 v[8:9], s[30:31], 0, v[32:33]
	v_mov_b32_e32 v131, v33
	v_readlane_b32 s26, v254, 14
	v_lshl_or_b32 v136, s10, 6, v7
	v_lshl_or_b32 v7, v7, 6, v17
	s_lshl_b32 s10, s10, 13
	v_and_b32_e32 v6, 32, v6
	s_lshl_b32 s5, s12, 7
	v_lshl_add_u64 v[10:11], s[30:31], 0, v[130:131]
	v_readlane_b32 s27, v254, 15
	v_bitop3_b32 v17, v7, s10, v6 bitop3:0xde
	v_bitop3_b32 v137, s5, v7, v6 bitop3:0xf6
	s_add_i32 m0, s36, 0x18000
	v_lshl_add_u64 v[6:7], v[8:9], 0, s[90:91]
	v_lshl_add_u64 v[12:13], s[26:27], 0, v[32:33]
	global_load_lds_dwordx4 v[6:7], off
	v_lshl_add_u64 v[6:7], v[10:11], 0, s[90:91]
	s_add_i32 m0, s36, 0x1a000
	s_add_i32 s40, s36, 0x8000
	s_add_i32 s41, s36, 0xa000
	v_lshl_add_u64 v[14:15], s[26:27], 0, v[130:131]
	global_load_lds_dwordx4 v[6:7], off
	v_lshl_add_u64 v[6:7], v[12:13], 0, s[90:91]
	s_mov_b32 m0, s40
	s_add_u32 s10, s30, 0x80080
	global_load_lds_dwordx4 v[6:7], off
	v_lshl_add_u64 v[6:7], v[14:15], 0, s[90:91]
	s_mov_b32 m0, s41
	s_addc_u32 s11, s31, 0
	global_load_lds_dwordx4 v[6:7], off
	s_add_i32 m0, s36, 0x1c000
	v_lshl_add_u64 v[6:7], s[10:11], 0, v[32:33]
	global_load_lds_dwordx4 v[6:7], off
	v_lshl_add_u64 v[6:7], s[10:11], 0, v[130:131]
	s_add_i32 m0, s36, 0x1e000
	s_cmpk_lt_u32 s4, 0x100
	global_load_lds_dwordx4 v[6:7], off
	s_waitcnt vmcnt(2)
	s_barrier
	v_lshlrev_b32_e32 v6, 15, v3
	v_and_b32_e32 v6, 0xffff0000, v6
	v_lshl_add_u32 v4, v4, 12, v6
	v_and_b32_e32 v3, 1, v3
	v_lshl_or_b32 v3, v3, 6, v4
	v_lshl_add_u32 v132, v5, 1, v3
	v_lshlrev_b32_e32 v3, 15, v0
	v_and_b32_e32 v3, 0xffff0000, v3
	s_waitcnt vmcnt(6)
	v_lshl_add_u32 v1, v1, 12, v3
	v_and_b32_e32 v0, 1, v0
	v_lshl_or_b32 v0, v0, 6, v1
	v_readlane_b32 s10, v254, 8
	v_readlane_b32 s14, v254, 10
	s_cselect_b64 s[4:5], -1, 0
	v_or_b32_e32 v138, s12, v16
	v_mov_b32_e32 v133, v33
	v_lshl_add_u32 v134, v2, 1, v0
	v_mov_b32_e32 v135, v33
	s_mov_b32 s42, 0
	v_add_u32_e32 v139, 0, v17
	s_mov_b32 s18, s10
	s_mov_b32 s19, s14
	s_barrier
	v_readlane_b32 s11, v254, 9
	v_readlane_b32 s15, v254, 11
	s_mov_b32 s60, 0
	s_branch .LBB0_1059

; #define GPROBE_BEGIN(id) do { if (((PROBE_GEMM_SEL >> (id)) & 1) && blockIdx.x == 0 && tid_in < 64 && g.N == 20480) { volatile PG8_LAS unsigned long long* PW_ = (volatile PG8_LAS unsigned long long*)(lds + 163840 - 512 + 64); PW_[0] = __builtin_amdgcn_s_memrealtime(); } } while (0)
; #define GPROBE_END(id) do { if (((PROBE_GEMM_SEL >> (id)) & 1) && blockIdx.x == 0 && tid_in < 64 && g.N == 20480) { volatile PG8_LAS unsigned long long* PW_ = (volatile PG8_LAS unsigned long long*)(lds + 163840 - 512 + 64); PW_[1] += __builtin_amdgcn_s_memrealtime() - PW_[0]; } } while (0)
; #define PG8_STAGE(bufoff, gbase, voff) do { _Pragma("unroll") for (int _i = 0; _i < 2; ++_i) \
;         __builtin_amdgcn_global_load_lds((const unsigned*)((const char*)(gbase) + (voff)[_i]), (PG8_LAS unsigned*)(lds + (bufoff) + ldsw + _i * 8192), 16, 0, 0); } while (0)
; template <class Epi, class Sched, bool ALIGN_EPI = false, bool SP2 = false, bool KHOOK = false>
; __device__ __forceinline__ void gemm_phase(PG8_LAS unsigned char* lds, const Gemm g, const Sched& S, const Epi& E, const int tid_in) {
;     ...
;         const bool has_next = S.next(ui + 1, nxt);
;         const char* nA = has_next ? (const char*)g.A + (size_t)nxt.pm * tstep + (size_t)nxt.pn * ksl : cA; const char* nB = has_next ? (const char*)g.Bt + (size_t)nxt.pn * bts + (size_t)nxt.pn * ksl + (gdv ? (size_t)(nxt.pm / gdv) * gst : 0) : cB;
;         GPROBE_END(2); GPROBE_BEGIN(1);
;         for (int t = 0; t < nt; t += 2) {
;             const bool last = (t == nt - 2);
;             const char* a1 = cA + (size_t)(t + 1) * kstep;
;             const char* a2 = last ? nA : cA + (size_t)(t + 2) * kstep; const char* b2 = last ? nB : cB + (size_t)(t + 2) * kstep;
;             const char* a3 = a2 + kstep; const char* b3 = b2 + kstep;
;             if (last && has_next) S.a_ready(nxt);
;             if constexpr (SP2) {
;             PG8_LDB(B0, 0, 0); PG8_LDB(B1, 0, 1); PG8_SCHED; PG8_LDA(At, 0, 0); PG8_STAGE(PG8_SA(1, 1), a1 + hstep, voffA);
;             PG8_WAIT_V(8); PG8_WAIT_L(0); PG8_BAR; PG8_MMA(0, 0, At, B0); PG8_MMA(0, 1, At, B1); PG8_BAR; PG8_SCHED;
;             PG8_LDA(At, 0, 1); PG8_STAGE(PG8_SB(0, 0), b2, voffB); PG8_STAGE(PG8_SB(0, 1), b2 + hstep, voffB); PG8_STAGE(PG8_SA(0, 0), a2, voffA);
;             PG8_WAIT_V(8); PG8_WAIT_L(0); PG8_BAR; PG8_MMA(1, 0, At, B0); PG8_MMA(1, 1, At, B1); PG8_BAR; PG8_SCHED;
.LBB0_1062:
	s_ashr_i32 s13, s12, 31
	s_lshl_b64 s[16:17], s[12:13], 20
	v_readlane_b32 s22, v254, 34
	v_readlane_b32 s23, v254, 35
	s_add_u32 s16, s22, s16
	s_addc_u32 s17, s23, s17
	s_and_b64 s[22:23], s[14:15], exec
	s_cselect_b32 s13, s17, s27
	s_cselect_b32 s24, s16, s26
	s_ashr_i32 s11, s10, 31
	s_lshl_b64 s[22:23], s[10:11], 20
	s_add_u32 s22, s2, s22
	s_addc_u32 s23, s20, s23
	s_and_b64 s[44:45], s[14:15], exec
	s_cselect_b32 s11, s23, s31
	s_cselect_b32 s25, s22, s30
	s_add_u32 s26, s26, 0x80080
	s_addc_u32 s27, s27, 0
	s_add_u32 s44, s30, 0x100
	s_addc_u32 s45, s31, 0
	s_mov_b32 s46, -2
	s_cmp_lg_u32 s60, 0
	s_cbranch_scc1 .Lg4_peel_h
	s_add_u32 s30, s26, 0xfff80080
	s_addc_u32 s31, s27, -1
	s_add_i32 s47, 0, 0x10000
	s_cmp_eq_u32 s46, 28
	s_cselect_b32 s49, s13, s31
	s_cselect_b32 s48, s24, s30
	s_cselect_b32 s31, s11, s45
	s_cselect_b32 s30, s25, s44
	s_add_i32 s52, 0, 0x14000
	v_add_u32_e32 v152, s47, v137
	v_add_u32_e32 v168, s52, v137
	ds_read_b128 v[140:143], v152
	ds_read_b128 v[144:147], v152 offset:1024
	ds_read_b128 v[148:151], v152 offset:2048
	ds_read_b128 v[152:155], v152 offset:3072
	ds_read_b128 v[156:159], v168
	ds_read_b128 v[160:163], v168 offset:1024
	ds_read_b128 v[164:167], v168 offset:2048
	ds_read_b128 v[168:171], v168 offset:3072
	v_lshl_add_u64 v[192:193], s[26:27], 0, v[132:133]
	s_add_i32 m0, s36, 0xc000
	ds_read_b128 v[172:175], v139
	ds_read_b128 v[176:179], v139 offset:1024
	ds_read_b128 v[180:183], v139 offset:2048
	ds_read_b128 v[184:187], v139 offset:3072
	ds_read_b128 v[188:191], v139 offset:4096
	ds_read_b128 v[198:201], v139 offset:5120
	ds_read_b128 v[202:205], v139 offset:6144
	ds_read_b128 v[206:209], v139 offset:7168
	global_load_lds_dwordx4 v[192:193], off
	v_lshl_add_u64 v[192:193], s[26:27], 0, v[134:135]
	s_add_i32 m0, s36, 0xe000
	s_nop 0
	global_load_lds_dwordx4 v[192:193], off
	s_waitcnt vmcnt(10)
	s_waitcnt lgkmcnt(0)
	s_barrier
	s_setprio 1
	s_waitcnt lgkmcnt(0)
	v_mfma_f32_16x16x32_bf16 v[126:129], v[140:143], v[172:175], 0
	v_mfma_f32_16x16x32_bf16 v[122:125], v[148:151], v[172:175], 0
	v_mfma_f32_16x16x32_bf16 v[110:113], v[140:143], v[180:183], 0
	v_mfma_f32_16x16x32_bf16 v[106:109], v[148:151], v[180:183], 0
	v_mfma_f32_16x16x32_bf16 v[94:97], v[140:143], v[188:191], 0
	v_mfma_f32_16x16x32_bf16 v[90:93], v[148:151], v[188:191], 0
	v_mfma_f32_16x16x32_bf16 v[78:81], v[140:143], v[202:205], 0
	v_mfma_f32_16x16x32_bf16 v[74:77], v[148:151], v[202:205], 0
	v_mfma_f32_16x16x32_bf16 v[126:129], v[144:147], v[176:179], v[126:129]
	v_mfma_f32_16x16x32_bf16 v[122:125], v[152:155], v[176:179], v[122:125]
	v_mfma_f32_16x16x32_bf16 v[110:113], v[144:147], v[184:187], v[110:113]
	v_mfma_f32_16x16x32_bf16 v[106:109], v[152:155], v[184:187], v[106:109]
	v_mfma_f32_16x16x32_bf16 v[94:97], v[144:147], v[198:201], v[94:97]
	v_mfma_f32_16x16x32_bf16 v[90:93], v[152:155], v[198:201], v[90:93]
	v_mfma_f32_16x16x32_bf16 v[78:81], v[144:147], v[206:209], v[78:81]
	v_mfma_f32_16x16x32_bf16 v[74:77], v[152:155], v[206:209], v[74:77]
	s_setprio 0
	s_setprio 1
	v_mfma_f32_16x16x32_bf16 v[118:121], v[156:159], v[172:175], 0
	v_mfma_f32_16x16x32_bf16 v[114:117], v[164:167], v[172:175], 0
	v_mfma_f32_16x16x32_bf16 v[102:105], v[156:159], v[180:183], 0
	v_mfma_f32_16x16x32_bf16 v[98:101], v[164:167], v[180:183], 0
	v_mfma_f32_16x16x32_bf16 v[86:89], v[156:159], v[188:191], 0
	v_mfma_f32_16x16x32_bf16 v[82:85], v[164:167], v[188:191], 0
	v_mfma_f32_16x16x32_bf16 v[70:73], v[156:159], v[202:205], 0
	v_mfma_f32_16x16x32_bf16 v[66:69], v[164:167], v[202:205], 0
	v_mfma_f32_16x16x32_bf16 v[118:121], v[160:163], v[176:179], v[118:121]
	v_mfma_f32_16x16x32_bf16 v[114:117], v[168:171], v[176:179], v[114:117]
	v_mfma_f32_16x16x32_bf16 v[102:105], v[160:163], v[184:187], v[102:105]
	v_mfma_f32_16x16x32_bf16 v[98:101], v[168:171], v[184:187], v[98:101]
	v_mfma_f32_16x16x32_bf16 v[86:89], v[160:163], v[198:201], v[86:89]
	v_mfma_f32_16x16x32_bf16 v[82:85], v[168:171], v[198:201], v[82:85]
	v_mfma_f32_16x16x32_bf16 v[70:73], v[160:163], v[206:209], v[70:73]
	v_mfma_f32_16x16x32_bf16 v[66:69], v[168:171], v[206:209], v[66:69]
	s_setprio 0
	s_barrier
	s_add_i32 s47, s47, s33
	v_lshl_add_u64 v[192:193], s[30:31], 0, v[32:33]
	s_mov_b32 m0, s47
	ds_read_b128 v[172:175], v139 offset:16384
	ds_read_b128 v[176:179], v139 offset:17408
	ds_read_b128 v[180:183], v139 offset:18432
	ds_read_b128 v[184:187], v139 offset:19456
	ds_read_b128 v[188:191], v139 offset:20480
	ds_read_b128 v[198:201], v139 offset:21504
	ds_read_b128 v[202:205], v139 offset:22528
	ds_read_b128 v[206:209], v139 offset:23552
	global_load_lds_dwordx4 v[192:193], off
	s_add_i32 m0, s47, 0x2000
	s_add_u32 s50, s30, 0x80000
	v_lshl_add_u64 v[210:211], s[30:31], 0, v[130:131]
	s_addc_u32 s51, s31, 0
	s_add_i32 s47, s52, s33
	global_load_lds_dwordx4 v[210:211], off
	v_lshl_add_u64 v[212:213], s[50:51], 0, v[32:33]
	s_mov_b32 m0, s47
	v_lshl_add_u64 v[214:215], s[48:49], 0, v[130:131]
	global_load_lds_dwordx4 v[212:213], off
	v_lshl_add_u64 v[212:213], s[50:51], 0, v[130:131]
	s_add_i32 m0, s47, 0x2000
	s_nop 0
	global_load_lds_dwordx4 v[212:213], off
	v_lshl_add_u64 v[212:213], s[48:49], 0, v[32:33]
	s_mov_b32 m0, s36
	s_nop 0
	global_load_lds_dwordx4 v[212:213], off
	s_mov_b32 m0, s37
	s_nop 0
	global_load_lds_dwordx4 v[214:215], off
	s_waitcnt vmcnt(16)
	s_waitcnt lgkmcnt(0)
	s_barrier
; #define PG8_STAGE(bufoff, gbase, voff) do { _Pragma("unroll") for (int _i = 0; _i < 2; ++_i) \
;         __builtin_amdgcn_global_load_lds((const unsigned*)((const char*)(gbase) + (voff)[_i]), (PG8_LAS unsigned*)(lds + (bufoff) + ldsw + _i * 8192), 16, 0, 0); } while (0)
; #define PG8_LDA(dst, b, h) do { _Pragma("unroll") for (int m = 0; m < 4; ++m) _Pragma("unroll") for (int k = 0; k < 2; ++k) dst[m][k] = *(const PG8_LAS bf16x8*)(lds + PG8_SA(b, h) + aoff + m * 2048 + k * 1024); } while (0)
; #define PG8_LDB(dst, b, h) do { _Pragma("unroll") for (int n = 0; n < 2; ++n) _Pragma("unroll") for (int k = 0; k < 2; ++k) dst[n][k] = *(const PG8_LAS bf16x8*)(lds + PG8_SB(b, h) + boff + n * 2048 + k * 1024); } while (0)
; #define PG8_MMA(ai, bj, At, Bt) do { __builtin_amdgcn_s_setprio(1); _Pragma("unroll") for (int m = 0; m < 4; ++m) _Pragma("unroll") for (int n = 0; n < 2; ++n) _Pragma("unroll") for (int k = 0; k < 2; ++k) \
;         acc[ai][bj][m][n] = __builtin_amdgcn_mfma_f32_16x16x32_bf16(Bt[n][k], At[m][k], acc[ai][bj][m][n], 0, 0, 0); __builtin_amdgcn_s_setprio(0); } while (0)
; #define PG8_WAIT_V(n) asm volatile("s_waitcnt vmcnt(" #n ")" ::: "memory")
; #define PG8_WAIT_L(n) asm volatile("s_waitcnt lgkmcnt(" #n ")" ::: "memory")
; #define PG8_BAR __builtin_amdgcn_s_barrier()
; #define PG8_SCHED __builtin_amdgcn_sched_barrier(0)
; template <class Epi, class Sched, bool ALIGN_EPI = false, bool SP2 = false, bool KHOOK = false>
; __device__ __forceinline__ void gemm_phase(PG8_LAS unsigned char* lds, const Gemm g, const Sched& S, const Epi& E, const int tid_in) {
;     ...
;             PG8_LDA(At, 0, 1); PG8_STAGE(PG8_SB(0, 0), b2, voffB); PG8_STAGE(PG8_SB(0, 1), b2 + hstep, voffB); PG8_STAGE(PG8_SA(0, 0), a2, voffA);
;             PG8_WAIT_V(8); PG8_WAIT_L(0); PG8_BAR; PG8_MMA(1, 0, At, B0); PG8_MMA(1, 1, At, B1); PG8_BAR; PG8_SCHED;
;             PG8_LDB(B0, 1, 0); PG8_LDB(B1, 1, 1); PG8_SCHED; PG8_LDA(At, 1, 0); PG8_STAGE(PG8_SA(0, 1), a2 + hstep, voffA);
;             PG8_WAIT_V(8); PG8_WAIT_L(0); PG8_BAR; PG8_MMA(0, 0, At, B0); PG8_MMA(0, 1, At, B1); PG8_BAR; PG8_SCHED;
	s_setprio 1
	s_waitcnt lgkmcnt(0)
	v_mfma_f32_16x16x32_bf16 v[62:65], v[140:143], v[172:175], 0
	v_mfma_f32_16x16x32_bf16 v[58:61], v[148:151], v[172:175], 0
	v_mfma_f32_16x16x32_bf16 v[46:49], v[140:143], v[180:183], 0
	v_mfma_f32_16x16x32_bf16 v[42:45], v[148:151], v[180:183], 0
	v_mfma_f32_16x16x32_bf16 v[28:31], v[140:143], v[188:191], 0
	v_mfma_f32_16x16x32_bf16 v[24:27], v[148:151], v[188:191], 0
	v_mfma_f32_16x16x32_bf16 v[12:15], v[140:143], v[202:205], 0
	v_mfma_f32_16x16x32_bf16 v[8:11], v[148:151], v[202:205], 0
	v_mfma_f32_16x16x32_bf16 v[62:65], v[144:147], v[176:179], v[62:65]
	v_mfma_f32_16x16x32_bf16 v[58:61], v[152:155], v[176:179], v[58:61]
	v_mfma_f32_16x16x32_bf16 v[46:49], v[144:147], v[184:187], v[46:49]
	v_mfma_f32_16x16x32_bf16 v[42:45], v[152:155], v[184:187], v[42:45]
	v_mfma_f32_16x16x32_bf16 v[28:31], v[144:147], v[198:201], v[28:31]
	v_mfma_f32_16x16x32_bf16 v[24:27], v[152:155], v[198:201], v[24:27]
	v_mfma_f32_16x16x32_bf16 v[12:15], v[144:147], v[206:209], v[12:15]
	v_mfma_f32_16x16x32_bf16 v[8:11], v[152:155], v[206:209], v[8:11]
	s_setprio 0
	s_setprio 1
	v_mfma_f32_16x16x32_bf16 v[54:57], v[156:159], v[172:175], 0
	v_mfma_f32_16x16x32_bf16 v[50:53], v[164:167], v[172:175], 0
	v_mfma_f32_16x16x32_bf16 v[38:41], v[156:159], v[180:183], 0
	v_mfma_f32_16x16x32_bf16 v[34:37], v[164:167], v[180:183], 0
	v_mfma_f32_16x16x32_bf16 v[20:23], v[156:159], v[188:191], 0
	v_mfma_f32_16x16x32_bf16 v[16:19], v[164:167], v[188:191], 0
	v_mfma_f32_16x16x32_bf16 v[4:7], v[156:159], v[202:205], 0
	v_mfma_f32_16x16x32_bf16 v[0:3], v[164:167], v[202:205], 0
	v_mfma_f32_16x16x32_bf16 v[54:57], v[160:163], v[176:179], v[54:57]
	v_mfma_f32_16x16x32_bf16 v[50:53], v[168:171], v[176:179], v[50:53]
	v_mfma_f32_16x16x32_bf16 v[38:41], v[160:163], v[184:187], v[38:41]
	v_mfma_f32_16x16x32_bf16 v[34:37], v[168:171], v[184:187], v[34:37]
	v_mfma_f32_16x16x32_bf16 v[20:23], v[160:163], v[198:201], v[20:23]
	v_mfma_f32_16x16x32_bf16 v[16:19], v[168:171], v[198:201], v[16:19]
	v_mfma_f32_16x16x32_bf16 v[4:7], v[160:163], v[206:209], v[4:7]
	v_mfma_f32_16x16x32_bf16 v[0:3], v[168:171], v[206:209], v[0:3]
	s_setprio 0
	s_barrier
	s_add_i32 s47, 0, 0x18000
	s_add_i32 s50, 0, 0x1c000
	v_add_u32_e32 v152, s47, v137
	v_add_u32_e32 v168, s50, v137
	ds_read_b128 v[140:143], v152
	ds_read_b128 v[144:147], v152 offset:1024
	ds_read_b128 v[148:151], v152 offset:2048
	ds_read_b128 v[152:155], v152 offset:3072
	ds_read_b128 v[156:159], v168
	ds_read_b128 v[160:163], v168 offset:1024
	ds_read_b128 v[164:167], v168 offset:2048
	ds_read_b128 v[168:171], v168 offset:3072
	s_add_u32 s48, s48, 0x80000
	s_addc_u32 s49, s49, 0
	s_mov_b32 m0, s38
	v_lshl_add_u64 v[216:217], s[48:49], 0, v[32:33]
	ds_read_b128 v[172:175], v139 offset:32768
	ds_read_b128 v[176:179], v139 offset:33792
	ds_read_b128 v[180:183], v139 offset:34816
	ds_read_b128 v[184:187], v139 offset:35840
	ds_read_b128 v[188:191], v139 offset:36864
	ds_read_b128 v[198:201], v139 offset:37888
	ds_read_b128 v[202:205], v139 offset:38912
	ds_read_b128 v[206:209], v139 offset:39936
	global_load_lds_dwordx4 v[216:217], off
	v_lshl_add_u64 v[216:217], s[48:49], 0, v[130:131]
	s_mov_b32 m0, s39
	s_nop 0
	global_load_lds_dwordx4 v[216:217], off
	s_waitcnt vmcnt(8)
	s_waitcnt lgkmcnt(0)
	s_barrier
	s_setprio 1
	s_waitcnt lgkmcnt(0)
	v_mfma_f32_16x16x32_bf16 v[126:129], v[140:143], v[172:175], v[126:129]
	v_mfma_f32_16x16x32_bf16 v[122:125], v[148:151], v[172:175], v[122:125]
	v_mfma_f32_16x16x32_bf16 v[110:113], v[140:143], v[180:183], v[110:113]
	v_mfma_f32_16x16x32_bf16 v[106:109], v[148:151], v[180:183], v[106:109]
	v_mfma_f32_16x16x32_bf16 v[94:97], v[140:143], v[188:191], v[94:97]
	v_mfma_f32_16x16x32_bf16 v[90:93], v[148:151], v[188:191], v[90:93]
	v_mfma_f32_16x16x32_bf16 v[78:81], v[140:143], v[202:205], v[78:81]
	v_mfma_f32_16x16x32_bf16 v[74:77], v[148:151], v[202:205], v[74:77]
	v_mfma_f32_16x16x32_bf16 v[126:129], v[144:147], v[176:179], v[126:129]
	v_mfma_f32_16x16x32_bf16 v[122:125], v[152:155], v[176:179], v[122:125]
	v_mfma_f32_16x16x32_bf16 v[110:113], v[144:147], v[184:187], v[110:113]
	v_mfma_f32_16x16x32_bf16 v[106:109], v[152:155], v[184:187], v[106:109]
	v_mfma_f32_16x16x32_bf16 v[94:97], v[144:147], v[198:201], v[94:97]
	v_mfma_f32_16x16x32_bf16 v[90:93], v[152:155], v[198:201], v[90:93]
	v_mfma_f32_16x16x32_bf16 v[78:81], v[144:147], v[206:209], v[78:81]
	v_mfma_f32_16x16x32_bf16 v[74:77], v[152:155], v[206:209], v[74:77]
	s_setprio 0
	s_setprio 1
	v_mfma_f32_16x16x32_bf16 v[118:121], v[156:159], v[172:175], v[118:121]
	v_mfma_f32_16x16x32_bf16 v[114:117], v[164:167], v[172:175], v[114:117]
	v_mfma_f32_16x16x32_bf16 v[102:105], v[156:159], v[180:183], v[102:105]
	v_mfma_f32_16x16x32_bf16 v[98:101], v[164:167], v[180:183], v[98:101]
	v_mfma_f32_16x16x32_bf16 v[86:89], v[156:159], v[188:191], v[86:89]
	v_mfma_f32_16x16x32_bf16 v[82:85], v[164:167], v[188:191], v[82:85]
	v_mfma_f32_16x16x32_bf16 v[70:73], v[156:159], v[202:205], v[70:73]
	v_mfma_f32_16x16x32_bf16 v[66:69], v[164:167], v[202:205], v[66:69]
	v_mfma_f32_16x16x32_bf16 v[118:121], v[160:163], v[176:179], v[118:121]
	v_mfma_f32_16x16x32_bf16 v[114:117], v[168:171], v[176:179], v[114:117]
	v_mfma_f32_16x16x32_bf16 v[102:105], v[160:163], v[184:187], v[102:105]
	v_mfma_f32_16x16x32_bf16 v[98:101], v[168:171], v[184:187], v[98:101]
	v_mfma_f32_16x16x32_bf16 v[86:89], v[160:163], v[198:201], v[86:89]
	v_mfma_f32_16x16x32_bf16 v[82:85], v[168:171], v[198:201], v[82:85]
	v_mfma_f32_16x16x32_bf16 v[70:73], v[160:163], v[206:209], v[70:73]
	v_mfma_f32_16x16x32_bf16 v[66:69], v[168:171], v[206:209], v[66:69]
	s_setprio 0
	s_barrier
; #define PG8_STAGE(bufoff, gbase, voff) do { _Pragma("unroll") for (int _i = 0; _i < 2; ++_i) \
;         __builtin_amdgcn_global_load_lds((const unsigned*)((const char*)(gbase) + (voff)[_i]), (PG8_LAS unsigned*)(lds + (bufoff) + ldsw + _i * 8192), 16, 0, 0); } while (0)
; #define PG8_LDA(dst, b, h) do { _Pragma("unroll") for (int m = 0; m < 4; ++m) _Pragma("unroll") for (int k = 0; k < 2; ++k) dst[m][k] = *(const PG8_LAS bf16x8*)(lds + PG8_SA(b, h) + aoff + m * 2048 + k * 1024); } while (0)
; #define PG8_LDB(dst, b, h) do { _Pragma("unroll") for (int n = 0; n < 2; ++n) _Pragma("unroll") for (int k = 0; k < 2; ++k) dst[n][k] = *(const PG8_LAS bf16x8*)(lds + PG8_SB(b, h) + boff + n * 2048 + k * 1024); } while (0)
; #define PG8_MMA(ai, bj, At, Bt) do { __builtin_amdgcn_s_setprio(1); _Pragma("unroll") for (int m = 0; m < 4; ++m) _Pragma("unroll") for (int n = 0; n < 2; ++n) _Pragma("unroll") for (int k = 0; k < 2; ++k) \
;         acc[ai][bj][m][n] = __builtin_amdgcn_mfma_f32_16x16x32_bf16(Bt[n][k], At[m][k], acc[ai][bj][m][n], 0, 0, 0); __builtin_amdgcn_s_setprio(0); } while (0)
; template <class Epi, class Sched, bool ALIGN_EPI = false, bool SP2 = false, bool KHOOK = false>
; __device__ __forceinline__ void gemm_phase(PG8_LAS unsigned char* lds, const Gemm g, const Sched& S, const Epi& E, const int tid_in) {
;     ...
;             PG8_LDB(B0, 0, 0); PG8_LDB(B1, 0, 1); PG8_SCHED; PG8_LDA(At, 0, 0); PG8_STAGE(PG8_SA(1, 1), a1 + hstep, voffA);
;             PG8_WAIT_V(8); PG8_WAIT_L(0); PG8_BAR; PG8_MMA(0, 0, At, B0); PG8_MMA(0, 1, At, B1); PG8_BAR; PG8_SCHED;
;             PG8_LDA(At, 0, 1); PG8_STAGE(PG8_SB(0, 0), b2, voffB); PG8_STAGE(PG8_SB(0, 1), b2 + hstep, voffB); PG8_STAGE(PG8_SA(0, 0), a2, voffA);
;             PG8_WAIT_V(8); PG8_WAIT_L(0); PG8_BAR; PG8_MMA(1, 0, At, B0); PG8_MMA(1, 1, At, B1); PG8_BAR; PG8_SCHED;
;             PG8_LDB(B0, 1, 0); PG8_LDB(B1, 1, 1); PG8_SCHED; PG8_LDA(At, 1, 0); PG8_STAGE(PG8_SA(0, 1), a2 + hstep, voffA);
;             PG8_WAIT_V(8); PG8_WAIT_L(0); PG8_BAR; PG8_MMA(0, 0, At, B0); PG8_MMA(0, 1, At, B1); PG8_BAR; PG8_SCHED;
;             PG8_LDA(At, 1, 1); PG8_STAGE(PG8_SB(1, 0), b3, voffB); PG8_STAGE(PG8_SB(1, 1), b3 + hstep, voffB); PG8_STAGE(PG8_SA(1, 0), a3, voffA);
;             PG8_WAIT_V(8); PG8_WAIT_L(0); PG8_BAR; PG8_MMA(1, 0, At, B0); PG8_MMA(1, 1, At, B1); PG8_BAR; PG8_SCHED;
	s_add_i32 s47, s47, s33
	v_lshl_add_u64 v[192:193], v[192:193], 0, s[90:91]
	s_mov_b32 m0, s47
	ds_read_b128 v[172:175], v139 offset:49152
	ds_read_b128 v[176:179], v139 offset:50176
	ds_read_b128 v[180:183], v139 offset:51200
	ds_read_b128 v[184:187], v139 offset:52224
	ds_read_b128 v[188:191], v139 offset:53248
	ds_read_b128 v[198:201], v139 offset:54272
	ds_read_b128 v[202:205], v139 offset:55296
	ds_read_b128 v[206:209], v139 offset:56320
	global_load_lds_dwordx4 v[192:193], off
	s_add_i32 m0, s47, 0x2000
	s_add_u32 s30, s30, 0x80080
	v_lshl_add_u64 v[192:193], v[210:211], 0, s[90:91]
	s_addc_u32 s31, s31, 0
	s_add_i32 s47, s50, s33
	global_load_lds_dwordx4 v[192:193], off
	v_lshl_add_u64 v[192:193], s[30:31], 0, v[32:33]
	s_mov_b32 m0, s47
	s_nop 0
	global_load_lds_dwordx4 v[192:193], off
	v_lshl_add_u64 v[192:193], s[30:31], 0, v[130:131]
	s_add_i32 m0, s47, 0x2000
	s_nop 0
	global_load_lds_dwordx4 v[192:193], off
	v_lshl_add_u64 v[192:193], v[212:213], 0, s[90:91]
	s_mov_b32 m0, s40
	s_nop 0
	global_load_lds_dwordx4 v[192:193], off
	v_lshl_add_u64 v[192:193], v[214:215], 0, s[90:91]
	s_mov_b32 m0, s41
	s_nop 0
	global_load_lds_dwordx4 v[192:193], off
	s_waitcnt vmcnt(8)
	s_waitcnt lgkmcnt(0)
	s_barrier
	s_setprio 1
	s_waitcnt lgkmcnt(0)
	v_mfma_f32_16x16x32_bf16 v[62:65], v[140:143], v[172:175], v[62:65]
	v_mfma_f32_16x16x32_bf16 v[58:61], v[148:151], v[172:175], v[58:61]
	v_mfma_f32_16x16x32_bf16 v[46:49], v[140:143], v[180:183], v[46:49]
	v_mfma_f32_16x16x32_bf16 v[42:45], v[148:151], v[180:183], v[42:45]
	v_mfma_f32_16x16x32_bf16 v[28:31], v[140:143], v[188:191], v[28:31]
	v_mfma_f32_16x16x32_bf16 v[24:27], v[148:151], v[188:191], v[24:27]
	v_mfma_f32_16x16x32_bf16 v[12:15], v[140:143], v[202:205], v[12:15]
	v_mfma_f32_16x16x32_bf16 v[8:11], v[148:151], v[202:205], v[8:11]
	v_mfma_f32_16x16x32_bf16 v[62:65], v[144:147], v[176:179], v[62:65]
	v_mfma_f32_16x16x32_bf16 v[58:61], v[152:155], v[176:179], v[58:61]
	v_mfma_f32_16x16x32_bf16 v[46:49], v[144:147], v[184:187], v[46:49]
	v_mfma_f32_16x16x32_bf16 v[42:45], v[152:155], v[184:187], v[42:45]
	v_mfma_f32_16x16x32_bf16 v[28:31], v[144:147], v[198:201], v[28:31]
	v_mfma_f32_16x16x32_bf16 v[24:27], v[152:155], v[198:201], v[24:27]
	v_mfma_f32_16x16x32_bf16 v[12:15], v[144:147], v[206:209], v[12:15]
	v_mfma_f32_16x16x32_bf16 v[8:11], v[152:155], v[206:209], v[8:11]
	s_setprio 0
	s_setprio 1
	v_mfma_f32_16x16x32_bf16 v[54:57], v[156:159], v[172:175], v[54:57]
	v_mfma_f32_16x16x32_bf16 v[50:53], v[164:167], v[172:175], v[50:53]
	v_mfma_f32_16x16x32_bf16 v[38:41], v[156:159], v[180:183], v[38:41]
	v_mfma_f32_16x16x32_bf16 v[34:37], v[164:167], v[180:183], v[34:37]
	v_mfma_f32_16x16x32_bf16 v[20:23], v[156:159], v[188:191], v[20:23]
	v_mfma_f32_16x16x32_bf16 v[16:19], v[164:167], v[188:191], v[16:19]
	v_mfma_f32_16x16x32_bf16 v[4:7], v[156:159], v[202:205], v[4:7]
	v_mfma_f32_16x16x32_bf16 v[0:3], v[164:167], v[202:205], v[0:3]
	v_mfma_f32_16x16x32_bf16 v[54:57], v[160:163], v[176:179], v[54:57]
	v_mfma_f32_16x16x32_bf16 v[50:53], v[168:171], v[176:179], v[50:53]
	v_mfma_f32_16x16x32_bf16 v[38:41], v[160:163], v[184:187], v[38:41]
	v_mfma_f32_16x16x32_bf16 v[34:37], v[168:171], v[184:187], v[34:37]
	v_mfma_f32_16x16x32_bf16 v[20:23], v[160:163], v[198:201], v[20:23]
	v_mfma_f32_16x16x32_bf16 v[16:19], v[168:171], v[198:201], v[16:19]
	v_mfma_f32_16x16x32_bf16 v[4:7], v[160:163], v[206:209], v[4:7]
	v_mfma_f32_16x16x32_bf16 v[0:3], v[168:171], v[206:209], v[0:3]
	s_setprio 0
	s_barrier
	s_add_i32 s46, s46, 2
	s_add_u32 s26, s26, 0x100
	s_addc_u32 s27, s27, 0
	s_add_u32 s44, s44, 0x100
	s_addc_u32 s45, s45, 0
	s_cmp_gt_u32 s46, 29
	s_branch .LBB0_1063
.Lg4_peel_h:
	s_add_u32 s30, s26, 0xfff80080
	s_addc_u32 s31, s27, -1
	s_add_i32 s47, 0, 0x10000
	s_cmp_eq_u32 s46, 28
	s_cselect_b32 s49, s13, s31
	s_cselect_b32 s48, s24, s30
	s_cselect_b32 s31, s11, s45
	s_cselect_b32 s30, s25, s44
	s_add_i32 s52, 0, 0x14000
	v_add_u32_e32 v152, s47, v137
	v_add_u32_e32 v168, s52, v137
	ds_read_b128 v[140:143], v152
	ds_read_b128 v[144:147], v152 offset:1024
	ds_read_b128 v[148:151], v152 offset:2048
	ds_read_b128 v[152:155], v152 offset:3072
	ds_read_b128 v[156:159], v168
	ds_read_b128 v[160:163], v168 offset:1024
	ds_read_b128 v[164:167], v168 offset:2048
	ds_read_b128 v[168:171], v168 offset:3072
	ds_read_b128 v[172:175], v139
	ds_read_b128 v[176:179], v139 offset:1024
	ds_read_b128 v[180:183], v139 offset:2048
	ds_read_b128 v[184:187], v139 offset:3072
	ds_read_b128 v[188:191], v139 offset:4096
	ds_read_b128 v[198:201], v139 offset:5120
	ds_read_b128 v[202:205], v139 offset:6144
	ds_read_b128 v[206:209], v139 offset:7168
	s_waitcnt vmcnt(10)
	s_waitcnt lgkmcnt(0)
	s_barrier
; #define PG8_STAGE(bufoff, gbase, voff) do { _Pragma("unroll") for (int _i = 0; _i < 2; ++_i) \
;         __builtin_amdgcn_global_load_lds((const unsigned*)((const char*)(gbase) + (voff)[_i]), (PG8_LAS unsigned*)(lds + (bufoff) + ldsw + _i * 8192), 16, 0, 0); } while (0)
; #define PG8_LDA(dst, b, h) do { _Pragma("unroll") for (int m = 0; m < 4; ++m) _Pragma("unroll") for (int k = 0; k < 2; ++k) dst[m][k] = *(const PG8_LAS bf16x8*)(lds + PG8_SA(b, h) + aoff + m * 2048 + k * 1024); } while (0)
; #define PG8_LDB(dst, b, h) do { _Pragma("unroll") for (int n = 0; n < 2; ++n) _Pragma("unroll") for (int k = 0; k < 2; ++k) dst[n][k] = *(const PG8_LAS bf16x8*)(lds + PG8_SB(b, h) + boff + n * 2048 + k * 1024); } while (0)
; #define PG8_MMA(ai, bj, At, Bt) do { __builtin_amdgcn_s_setprio(1); _Pragma("unroll") for (int m = 0; m < 4; ++m) _Pragma("unroll") for (int n = 0; n < 2; ++n) _Pragma("unroll") for (int k = 0; k < 2; ++k) \
;         acc[ai][bj][m][n] = __builtin_amdgcn_mfma_f32_16x16x32_bf16(Bt[n][k], At[m][k], acc[ai][bj][m][n], 0, 0, 0); __builtin_amdgcn_s_setprio(0); } while (0)
; #define PG8_WAIT_V(n) asm volatile("s_waitcnt vmcnt(" #n ")" ::: "memory")
; #define PG8_WAIT_L(n) asm volatile("s_waitcnt lgkmcnt(" #n ")" ::: "memory")
; #define PG8_BAR __builtin_amdgcn_s_barrier()
; #define PG8_SCHED __builtin_amdgcn_sched_barrier(0)
; template <class Epi, class Sched, bool ALIGN_EPI = false, bool SP2 = false, bool KHOOK = false>
; __device__ __forceinline__ void gemm_phase(PG8_LAS unsigned char* lds, const Gemm g, const Sched& S, const Epi& E, const int tid_in) {
;     ...
;             PG8_WAIT_V(8); PG8_WAIT_L(0); PG8_BAR; PG8_MMA(0, 0, At, B0); PG8_MMA(0, 1, At, B1); PG8_BAR; PG8_SCHED;
;             PG8_LDA(At, 0, 1); PG8_STAGE(PG8_SB(0, 0), b2, voffB); PG8_STAGE(PG8_SB(0, 1), b2 + hstep, voffB); PG8_STAGE(PG8_SA(0, 0), a2, voffA);
;             PG8_WAIT_V(8); PG8_WAIT_L(0); PG8_BAR; PG8_MMA(1, 0, At, B0); PG8_MMA(1, 1, At, B1); PG8_BAR; PG8_SCHED;
;             PG8_LDB(B0, 1, 0); PG8_LDB(B1, 1, 1); PG8_SCHED; PG8_LDA(At, 1, 0); PG8_STAGE(PG8_SA(0, 1), a2 + hstep, voffA);
;             PG8_WAIT_V(8); PG8_WAIT_L(0); PG8_BAR; PG8_MMA(0, 0, At, B0); PG8_MMA(0, 1, At, B1); PG8_BAR; PG8_SCHED;
	s_setprio 1
	s_waitcnt lgkmcnt(0)
	v_mfma_f32_16x16x32_bf16 v[126:129], v[140:143], v[172:175], 0
	v_mfma_f32_16x16x32_bf16 v[122:125], v[148:151], v[172:175], 0
	v_mfma_f32_16x16x32_bf16 v[110:113], v[140:143], v[180:183], 0
	v_mfma_f32_16x16x32_bf16 v[106:109], v[148:151], v[180:183], 0
	v_mfma_f32_16x16x32_bf16 v[94:97], v[140:143], v[188:191], 0
	v_mfma_f32_16x16x32_bf16 v[90:93], v[148:151], v[188:191], 0
	v_mfma_f32_16x16x32_bf16 v[78:81], v[140:143], v[202:205], 0
	v_mfma_f32_16x16x32_bf16 v[74:77], v[148:151], v[202:205], 0
	v_mfma_f32_16x16x32_bf16 v[126:129], v[144:147], v[176:179], v[126:129]
	v_mfma_f32_16x16x32_bf16 v[122:125], v[152:155], v[176:179], v[122:125]
	v_mfma_f32_16x16x32_bf16 v[110:113], v[144:147], v[184:187], v[110:113]
	v_mfma_f32_16x16x32_bf16 v[106:109], v[152:155], v[184:187], v[106:109]
	v_mfma_f32_16x16x32_bf16 v[94:97], v[144:147], v[198:201], v[94:97]
	v_mfma_f32_16x16x32_bf16 v[90:93], v[152:155], v[198:201], v[90:93]
	v_mfma_f32_16x16x32_bf16 v[78:81], v[144:147], v[206:209], v[78:81]
	v_mfma_f32_16x16x32_bf16 v[74:77], v[152:155], v[206:209], v[74:77]
	s_setprio 0
	s_setprio 1
	v_mfma_f32_16x16x32_bf16 v[118:121], v[156:159], v[172:175], 0
	v_mfma_f32_16x16x32_bf16 v[114:117], v[164:167], v[172:175], 0
	v_mfma_f32_16x16x32_bf16 v[102:105], v[156:159], v[180:183], 0
	v_mfma_f32_16x16x32_bf16 v[98:101], v[164:167], v[180:183], 0
	v_mfma_f32_16x16x32_bf16 v[86:89], v[156:159], v[188:191], 0
	v_mfma_f32_16x16x32_bf16 v[82:85], v[164:167], v[188:191], 0
	v_mfma_f32_16x16x32_bf16 v[70:73], v[156:159], v[202:205], 0
	v_mfma_f32_16x16x32_bf16 v[66:69], v[164:167], v[202:205], 0
	v_mfma_f32_16x16x32_bf16 v[118:121], v[160:163], v[176:179], v[118:121]
	v_mfma_f32_16x16x32_bf16 v[114:117], v[168:171], v[176:179], v[114:117]
	v_mfma_f32_16x16x32_bf16 v[102:105], v[160:163], v[184:187], v[102:105]
	v_mfma_f32_16x16x32_bf16 v[98:101], v[168:171], v[184:187], v[98:101]
	v_mfma_f32_16x16x32_bf16 v[86:89], v[160:163], v[198:201], v[86:89]
	v_mfma_f32_16x16x32_bf16 v[82:85], v[168:171], v[198:201], v[82:85]
	v_mfma_f32_16x16x32_bf16 v[70:73], v[160:163], v[206:209], v[70:73]
	v_mfma_f32_16x16x32_bf16 v[66:69], v[168:171], v[206:209], v[66:69]
	s_setprio 0
	s_barrier
	s_add_i32 s47, s47, s33
	v_lshl_add_u64 v[192:193], s[30:31], 0, v[32:33]
	s_mov_b32 m0, s47
	ds_read_b128 v[172:175], v139 offset:16384
	ds_read_b128 v[176:179], v139 offset:17408
	ds_read_b128 v[180:183], v139 offset:18432
	ds_read_b128 v[184:187], v139 offset:19456
	ds_read_b128 v[188:191], v139 offset:20480
	ds_read_b128 v[198:201], v139 offset:21504
	ds_read_b128 v[202:205], v139 offset:22528
	ds_read_b128 v[206:209], v139 offset:23552
	global_load_lds_dwordx4 v[192:193], off
	s_add_i32 m0, s47, 0x2000
	s_add_u32 s50, s30, 0x80000
	v_lshl_add_u64 v[210:211], s[30:31], 0, v[130:131]
	s_addc_u32 s51, s31, 0
	s_add_i32 s47, s52, s33
	global_load_lds_dwordx4 v[210:211], off
	v_lshl_add_u64 v[212:213], s[50:51], 0, v[32:33]
	s_mov_b32 m0, s47
	v_lshl_add_u64 v[214:215], s[48:49], 0, v[130:131]
	global_load_lds_dwordx4 v[212:213], off
	v_lshl_add_u64 v[212:213], s[50:51], 0, v[130:131]
	s_add_i32 m0, s47, 0x2000
	s_nop 0
	global_load_lds_dwordx4 v[212:213], off
	v_lshl_add_u64 v[212:213], s[48:49], 0, v[32:33]
	s_mov_b32 m0, s36
	s_nop 0
	global_load_lds_dwordx4 v[212:213], off
	s_mov_b32 m0, s37
	s_nop 0
	global_load_lds_dwordx4 v[214:215], off
	s_waitcnt vmcnt(16)
	s_waitcnt lgkmcnt(0)
	s_barrier
	s_setprio 1
	s_waitcnt lgkmcnt(0)
	v_mfma_f32_16x16x32_bf16 v[62:65], v[140:143], v[172:175], 0
	v_mfma_f32_16x16x32_bf16 v[58:61], v[148:151], v[172:175], 0
	v_mfma_f32_16x16x32_bf16 v[46:49], v[140:143], v[180:183], 0
	v_mfma_f32_16x16x32_bf16 v[42:45], v[148:151], v[180:183], 0
	v_mfma_f32_16x16x32_bf16 v[28:31], v[140:143], v[188:191], 0
	v_mfma_f32_16x16x32_bf16 v[24:27], v[148:151], v[188:191], 0
	v_mfma_f32_16x16x32_bf16 v[12:15], v[140:143], v[202:205], 0
	v_mfma_f32_16x16x32_bf16 v[8:11], v[148:151], v[202:205], 0
	v_mfma_f32_16x16x32_bf16 v[62:65], v[144:147], v[176:179], v[62:65]
	v_mfma_f32_16x16x32_bf16 v[58:61], v[152:155], v[176:179], v[58:61]
	v_mfma_f32_16x16x32_bf16 v[46:49], v[144:147], v[184:187], v[46:49]
	v_mfma_f32_16x16x32_bf16 v[42:45], v[152:155], v[184:187], v[42:45]
	v_mfma_f32_16x16x32_bf16 v[28:31], v[144:147], v[198:201], v[28:31]
	v_mfma_f32_16x16x32_bf16 v[24:27], v[152:155], v[198:201], v[24:27]
	v_mfma_f32_16x16x32_bf16 v[12:15], v[144:147], v[206:209], v[12:15]
	v_mfma_f32_16x16x32_bf16 v[8:11], v[152:155], v[206:209], v[8:11]
	s_setprio 0
	s_setprio 1
	v_mfma_f32_16x16x32_bf16 v[54:57], v[156:159], v[172:175], 0
	v_mfma_f32_16x16x32_bf16 v[50:53], v[164:167], v[172:175], 0
	v_mfma_f32_16x16x32_bf16 v[38:41], v[156:159], v[180:183], 0
	v_mfma_f32_16x16x32_bf16 v[34:37], v[164:167], v[180:183], 0
	v_mfma_f32_16x16x32_bf16 v[20:23], v[156:159], v[188:191], 0
	v_mfma_f32_16x16x32_bf16 v[16:19], v[164:167], v[188:191], 0
	v_mfma_f32_16x16x32_bf16 v[4:7], v[156:159], v[202:205], 0
	v_mfma_f32_16x16x32_bf16 v[0:3], v[164:167], v[202:205], 0
	v_mfma_f32_16x16x32_bf16 v[54:57], v[160:163], v[176:179], v[54:57]
	v_mfma_f32_16x16x32_bf16 v[50:53], v[168:171], v[176:179], v[50:53]
	v_mfma_f32_16x16x32_bf16 v[38:41], v[160:163], v[184:187], v[38:41]
	v_mfma_f32_16x16x32_bf16 v[34:37], v[168:171], v[184:187], v[34:37]
	v_mfma_f32_16x16x32_bf16 v[20:23], v[160:163], v[198:201], v[20:23]
	v_mfma_f32_16x16x32_bf16 v[16:19], v[168:171], v[198:201], v[16:19]
	v_mfma_f32_16x16x32_bf16 v[4:7], v[160:163], v[206:209], v[4:7]
	v_mfma_f32_16x16x32_bf16 v[0:3], v[168:171], v[206:209], v[0:3]
	s_setprio 0
	s_barrier
; #define PG8_STAGE(bufoff, gbase, voff) do { _Pragma("unroll") for (int _i = 0; _i < 2; ++_i) \
;         __builtin_amdgcn_global_load_lds((const unsigned*)((const char*)(gbase) + (voff)[_i]), (PG8_LAS unsigned*)(lds + (bufoff) + ldsw + _i * 8192), 16, 0, 0); } while (0)
; #define PG8_LDA(dst, b, h) do { _Pragma("unroll") for (int m = 0; m < 4; ++m) _Pragma("unroll") for (int k = 0; k < 2; ++k) dst[m][k] = *(const PG8_LAS bf16x8*)(lds + PG8_SA(b, h) + aoff + m * 2048 + k * 1024); } while (0)
; #define PG8_LDB(dst, b, h) do { _Pragma("unroll") for (int n = 0; n < 2; ++n) _Pragma("unroll") for (int k = 0; k < 2; ++k) dst[n][k] = *(const PG8_LAS bf16x8*)(lds + PG8_SB(b, h) + boff + n * 2048 + k * 1024); } while (0)
; #define PG8_MMA(ai, bj, At, Bt) do { __builtin_amdgcn_s_setprio(1); _Pragma("unroll") for (int m = 0; m < 4; ++m) _Pragma("unroll") for (int n = 0; n < 2; ++n) _Pragma("unroll") for (int k = 0; k < 2; ++k) \
;         acc[ai][bj][m][n] = __builtin_amdgcn_mfma_f32_16x16x32_bf16(Bt[n][k], At[m][k], acc[ai][bj][m][n], 0, 0, 0); __builtin_amdgcn_s_setprio(0); } while (0)
; #define PG8_WAIT_V(n) asm volatile("s_waitcnt vmcnt(" #n ")" ::: "memory")
; #define PG8_WAIT_L(n) asm volatile("s_waitcnt lgkmcnt(" #n ")" ::: "memory")
; #define PG8_BAR __builtin_amdgcn_s_barrier()
; #define PG8_SCHED __builtin_amdgcn_sched_barrier(0)
; template <class Epi, class Sched, bool ALIGN_EPI = false, bool SP2 = false, bool KHOOK = false>
; __device__ __forceinline__ void gemm_phase(PG8_LAS unsigned char* lds, const Gemm g, const Sched& S, const Epi& E, const int tid_in) {
;     ...
;             PG8_LDB(B0, 1, 0); PG8_LDB(B1, 1, 1); PG8_SCHED; PG8_LDA(At, 1, 0); PG8_STAGE(PG8_SA(0, 1), a2 + hstep, voffA);
;             PG8_WAIT_V(8); PG8_WAIT_L(0); PG8_BAR; PG8_MMA(0, 0, At, B0); PG8_MMA(0, 1, At, B1); PG8_BAR; PG8_SCHED;
	s_add_i32 s47, 0, 0x18000
	s_add_i32 s50, 0, 0x1c000
	v_add_u32_e32 v152, s47, v137
	v_add_u32_e32 v168, s50, v137
	ds_read_b128 v[140:143], v152
	ds_read_b128 v[144:147], v152 offset:1024
	ds_read_b128 v[148:151], v152 offset:2048
	ds_read_b128 v[152:155], v152 offset:3072
	ds_read_b128 v[156:159], v168
	ds_read_b128 v[160:163], v168 offset:1024
	ds_read_b128 v[164:167], v168 offset:2048
	ds_read_b128 v[168:171], v168 offset:3072
	s_add_u32 s48, s48, 0x80000
	s_addc_u32 s49, s49, 0
	s_mov_b32 m0, s38
	v_lshl_add_u64 v[216:217], s[48:49], 0, v[32:33]
	ds_read_b128 v[172:175], v139 offset:32768
	ds_read_b128 v[176:179], v139 offset:33792
	ds_read_b128 v[180:183], v139 offset:34816
	ds_read_b128 v[184:187], v139 offset:35840
	ds_read_b128 v[188:191], v139 offset:36864
	ds_read_b128 v[198:201], v139 offset:37888
	ds_read_b128 v[202:205], v139 offset:38912
	ds_read_b128 v[206:209], v139 offset:39936
	global_load_lds_dwordx4 v[216:217], off
	v_lshl_add_u64 v[216:217], s[48:49], 0, v[130:131]
	s_mov_b32 m0, s39
	s_nop 0
	global_load_lds_dwordx4 v[216:217], off
	s_waitcnt vmcnt(16)
	s_waitcnt lgkmcnt(0)
	s_barrier
	s_setprio 1
	s_waitcnt lgkmcnt(0)
	v_mfma_f32_16x16x32_bf16 v[126:129], v[140:143], v[172:175], v[126:129]
	v_mfma_f32_16x16x32_bf16 v[122:125], v[148:151], v[172:175], v[122:125]
	v_mfma_f32_16x16x32_bf16 v[110:113], v[140:143], v[180:183], v[110:113]
	v_mfma_f32_16x16x32_bf16 v[106:109], v[148:151], v[180:183], v[106:109]
	v_mfma_f32_16x16x32_bf16 v[94:97], v[140:143], v[188:191], v[94:97]
	v_mfma_f32_16x16x32_bf16 v[90:93], v[148:151], v[188:191], v[90:93]
	v_mfma_f32_16x16x32_bf16 v[78:81], v[140:143], v[202:205], v[78:81]
	v_mfma_f32_16x16x32_bf16 v[74:77], v[148:151], v[202:205], v[74:77]
	v_mfma_f32_16x16x32_bf16 v[126:129], v[144:147], v[176:179], v[126:129]
	v_mfma_f32_16x16x32_bf16 v[122:125], v[152:155], v[176:179], v[122:125]
	v_mfma_f32_16x16x32_bf16 v[110:113], v[144:147], v[184:187], v[110:113]
	v_mfma_f32_16x16x32_bf16 v[106:109], v[152:155], v[184:187], v[106:109]
	v_mfma_f32_16x16x32_bf16 v[94:97], v[144:147], v[198:201], v[94:97]
	v_mfma_f32_16x16x32_bf16 v[90:93], v[152:155], v[198:201], v[90:93]
	v_mfma_f32_16x16x32_bf16 v[78:81], v[144:147], v[206:209], v[78:81]
	v_mfma_f32_16x16x32_bf16 v[74:77], v[152:155], v[206:209], v[74:77]
	s_setprio 0
	s_setprio 1
	v_mfma_f32_16x16x32_bf16 v[118:121], v[156:159], v[172:175], v[118:121]
	v_mfma_f32_16x16x32_bf16 v[114:117], v[164:167], v[172:175], v[114:117]
	v_mfma_f32_16x16x32_bf16 v[102:105], v[156:159], v[180:183], v[102:105]
	v_mfma_f32_16x16x32_bf16 v[98:101], v[164:167], v[180:183], v[98:101]
	v_mfma_f32_16x16x32_bf16 v[86:89], v[156:159], v[188:191], v[86:89]
	v_mfma_f32_16x16x32_bf16 v[82:85], v[164:167], v[188:191], v[82:85]
	v_mfma_f32_16x16x32_bf16 v[70:73], v[156:159], v[202:205], v[70:73]
	v_mfma_f32_16x16x32_bf16 v[66:69], v[164:167], v[202:205], v[66:69]
	v_mfma_f32_16x16x32_bf16 v[118:121], v[160:163], v[176:179], v[118:121]
	v_mfma_f32_16x16x32_bf16 v[114:117], v[168:171], v[176:179], v[114:117]
	v_mfma_f32_16x16x32_bf16 v[102:105], v[160:163], v[184:187], v[102:105]
	v_mfma_f32_16x16x32_bf16 v[98:101], v[168:171], v[184:187], v[98:101]
	v_mfma_f32_16x16x32_bf16 v[86:89], v[160:163], v[198:201], v[86:89]
	v_mfma_f32_16x16x32_bf16 v[82:85], v[168:171], v[198:201], v[82:85]
	v_mfma_f32_16x16x32_bf16 v[70:73], v[160:163], v[206:209], v[70:73]
	v_mfma_f32_16x16x32_bf16 v[66:69], v[168:171], v[206:209], v[66:69]
	s_setprio 0
	s_barrier
; #define PG8_STAGE(bufoff, gbase, voff) do { _Pragma("unroll") for (int _i = 0; _i < 2; ++_i) \
;         __builtin_amdgcn_global_load_lds((const unsigned*)((const char*)(gbase) + (voff)[_i]), (PG8_LAS unsigned*)(lds + (bufoff) + ldsw + _i * 8192), 16, 0, 0); } while (0)
; #define PG8_LDA(dst, b, h) do { _Pragma("unroll") for (int m = 0; m < 4; ++m) _Pragma("unroll") for (int k = 0; k < 2; ++k) dst[m][k] = *(const PG8_LAS bf16x8*)(lds + PG8_SA(b, h) + aoff + m * 2048 + k * 1024); } while (0)
; #define PG8_MMA(ai, bj, At, Bt) do { __builtin_amdgcn_s_setprio(1); _Pragma("unroll") for (int m = 0; m < 4; ++m) _Pragma("unroll") for (int n = 0; n < 2; ++n) _Pragma("unroll") for (int k = 0; k < 2; ++k) \
;         acc[ai][bj][m][n] = __builtin_amdgcn_mfma_f32_16x16x32_bf16(Bt[n][k], At[m][k], acc[ai][bj][m][n], 0, 0, 0); __builtin_amdgcn_s_setprio(0); } while (0)
; #define PG8_WAIT_V(n) asm volatile("s_waitcnt vmcnt(" #n ")" ::: "memory")
; #define PG8_WAIT_L(n) asm volatile("s_waitcnt lgkmcnt(" #n ")" ::: "memory")
; #define PG8_BAR __builtin_amdgcn_s_barrier()
; #define PG8_SCHED __builtin_amdgcn_sched_barrier(0)
; template <class Epi, class Sched, bool ALIGN_EPI = false, bool SP2 = false, bool KHOOK = false>
; __device__ __forceinline__ void gemm_phase(PG8_LAS unsigned char* lds, const Gemm g, const Sched& S, const Epi& E, const int tid_in) {
;     ...
;             PG8_LDA(At, 1, 1); PG8_STAGE(PG8_SB(1, 0), b3, voffB); PG8_STAGE(PG8_SB(1, 1), b3 + hstep, voffB); PG8_STAGE(PG8_SA(1, 0), a3, voffA);
;             PG8_WAIT_V(8); PG8_WAIT_L(0); PG8_BAR; PG8_MMA(1, 0, At, B0); PG8_MMA(1, 1, At, B1); PG8_BAR; PG8_SCHED;
	s_add_i32 s47, s47, s33
	v_lshl_add_u64 v[192:193], v[192:193], 0, s[90:91]
	s_mov_b32 m0, s47
	ds_read_b128 v[172:175], v139 offset:49152
	ds_read_b128 v[176:179], v139 offset:50176
	ds_read_b128 v[180:183], v139 offset:51200
	ds_read_b128 v[184:187], v139 offset:52224
	ds_read_b128 v[188:191], v139 offset:53248
	ds_read_b128 v[198:201], v139 offset:54272
	ds_read_b128 v[202:205], v139 offset:55296
	ds_read_b128 v[206:209], v139 offset:56320
	global_load_lds_dwordx4 v[192:193], off
	s_add_i32 m0, s47, 0x2000
	s_add_u32 s30, s30, 0x80080
	v_lshl_add_u64 v[192:193], v[210:211], 0, s[90:91]
	s_addc_u32 s31, s31, 0
	s_add_i32 s47, s50, s33
	global_load_lds_dwordx4 v[192:193], off
	v_lshl_add_u64 v[192:193], s[30:31], 0, v[32:33]
	s_mov_b32 m0, s47
	s_nop 0
	global_load_lds_dwordx4 v[192:193], off
	v_lshl_add_u64 v[192:193], s[30:31], 0, v[130:131]
	s_add_i32 m0, s47, 0x2000
	s_nop 0
	global_load_lds_dwordx4 v[192:193], off
	v_lshl_add_u64 v[192:193], v[212:213], 0, s[90:91]
	s_mov_b32 m0, s40
	s_nop 0
	global_load_lds_dwordx4 v[192:193], off
	v_lshl_add_u64 v[192:193], v[214:215], 0, s[90:91]
	s_mov_b32 m0, s41
	s_nop 0
	global_load_lds_dwordx4 v[192:193], off
	s_waitcnt vmcnt(8)
	s_waitcnt lgkmcnt(0)
	s_barrier
	s_setprio 1
	s_waitcnt lgkmcnt(0)
	v_mfma_f32_16x16x32_bf16 v[62:65], v[140:143], v[172:175], v[62:65]
	v_mfma_f32_16x16x32_bf16 v[58:61], v[148:151], v[172:175], v[58:61]
	v_mfma_f32_16x16x32_bf16 v[46:49], v[140:143], v[180:183], v[46:49]
	v_mfma_f32_16x16x32_bf16 v[42:45], v[148:151], v[180:183], v[42:45]
	v_mfma_f32_16x16x32_bf16 v[28:31], v[140:143], v[188:191], v[28:31]
	v_mfma_f32_16x16x32_bf16 v[24:27], v[148:151], v[188:191], v[24:27]
	v_mfma_f32_16x16x32_bf16 v[12:15], v[140:143], v[202:205], v[12:15]
	v_mfma_f32_16x16x32_bf16 v[8:11], v[148:151], v[202:205], v[8:11]
	v_mfma_f32_16x16x32_bf16 v[62:65], v[144:147], v[176:179], v[62:65]
	v_mfma_f32_16x16x32_bf16 v[58:61], v[152:155], v[176:179], v[58:61]
	v_mfma_f32_16x16x32_bf16 v[46:49], v[144:147], v[184:187], v[46:49]
	v_mfma_f32_16x16x32_bf16 v[42:45], v[152:155], v[184:187], v[42:45]
	v_mfma_f32_16x16x32_bf16 v[28:31], v[144:147], v[198:201], v[28:31]
	v_mfma_f32_16x16x32_bf16 v[24:27], v[152:155], v[198:201], v[24:27]
	v_mfma_f32_16x16x32_bf16 v[12:15], v[144:147], v[206:209], v[12:15]
	v_mfma_f32_16x16x32_bf16 v[8:11], v[152:155], v[206:209], v[8:11]
	s_setprio 0
	s_setprio 1
	v_mfma_f32_16x16x32_bf16 v[54:57], v[156:159], v[172:175], v[54:57]
	v_mfma_f32_16x16x32_bf16 v[50:53], v[164:167], v[172:175], v[50:53]
	v_mfma_f32_16x16x32_bf16 v[38:41], v[156:159], v[180:183], v[38:41]
	v_mfma_f32_16x16x32_bf16 v[34:37], v[164:167], v[180:183], v[34:37]
	v_mfma_f32_16x16x32_bf16 v[20:23], v[156:159], v[188:191], v[20:23]
	v_mfma_f32_16x16x32_bf16 v[16:19], v[164:167], v[188:191], v[16:19]
	v_mfma_f32_16x16x32_bf16 v[4:7], v[156:159], v[202:205], v[4:7]
	v_mfma_f32_16x16x32_bf16 v[0:3], v[164:167], v[202:205], v[0:3]
	v_mfma_f32_16x16x32_bf16 v[54:57], v[160:163], v[176:179], v[54:57]
	v_mfma_f32_16x16x32_bf16 v[50:53], v[168:171], v[176:179], v[50:53]
	v_mfma_f32_16x16x32_bf16 v[38:41], v[160:163], v[184:187], v[38:41]
	v_mfma_f32_16x16x32_bf16 v[34:37], v[168:171], v[184:187], v[34:37]
	v_mfma_f32_16x16x32_bf16 v[20:23], v[160:163], v[198:201], v[20:23]
	v_mfma_f32_16x16x32_bf16 v[16:19], v[168:171], v[198:201], v[16:19]
	v_mfma_f32_16x16x32_bf16 v[4:7], v[160:163], v[206:209], v[4:7]
	v_mfma_f32_16x16x32_bf16 v[0:3], v[168:171], v[206:209], v[0:3]
	s_setprio 0
	s_barrier
	s_add_i32 s46, s46, 2
	s_add_u32 s26, s26, 0x100
	s_addc_u32 s27, s27, 0
	s_add_u32 s44, s44, 0x100
	s_addc_u32 s45, s45, 0
	s_cmp_gt_u32 s46, 29

; __device__ __forceinline__ unsigned cvt_pk_bf16(float lo, float hi) { const f32x2_t v = {lo, hi}; const bf16x2_t c = __builtin_convertvector(v, bf16x2_t); return __builtin_bit_cast(unsigned, c); }
; __device__ __forceinline__ float siluf_fast(float x) { return x * sigmoidf_fast(x); }
; #define PG8_STAGE(bufoff, gbase, voff) do { _Pragma("unroll") for (int _i = 0; _i < 2; ++_i) \
;         __builtin_amdgcn_global_load_lds((const unsigned*)((const char*)(gbase) + (voff)[_i]), (PG8_LAS unsigned*)(lds + (bufoff) + ldsw + _i * 8192), 16, 0, 0); } while (0)
; #define PG8_LDA(dst, b, h) do { _Pragma("unroll") for (int m = 0; m < 4; ++m) _Pragma("unroll") for (int k = 0; k < 2; ++k) dst[m][k] = *(const PG8_LAS bf16x8*)(lds + PG8_SA(b, h) + aoff + m * 2048 + k * 1024); } while (0)
; #define PG8_LDB(dst, b, h) do { _Pragma("unroll") for (int n = 0; n < 2; ++n) _Pragma("unroll") for (int k = 0; k < 2; ++k) dst[n][k] = *(const PG8_LAS bf16x8*)(lds + PG8_SB(b, h) + boff + n * 2048 + k * 1024); } while (0)
; #define PG8_SCHED __builtin_amdgcn_sched_barrier(0)
;     __device__ __forceinline__ void operator()(const f32x4 (&acc)[2][2][4][2], const Unit& u, int wr, int wc, int fr, int fq) const {
;         const int row0 = u.pm * BM + wr * 64 + fr, col0 = u.pn * HALF + wc * 32 + 8 * fq;
; #pragma unroll
;         for (int ai = 0; ai < 2; ++ai)
; #pragma unroll
;             for (int m = 0; m < 4; ++m) { const size_t r = (size_t)(row0 + ai * HALF + m * 16);
;                 const f32x4 g0 = acc[ai][0][m][0], u0 = acc[ai][0][m][1], g1 = acc[ai][1][m][0], u1 = acc[ai][1][m][1];
;                 u32x4 w; w.x = cvt_pk_bf16(siluf_fast(g0[0]) * u0[0], siluf_fast(g0[1]) * u0[1]); w.y = cvt_pk_bf16(siluf_fast(g0[2]) * u0[2], siluf_fast(g0[3]) * u0[3]);
;                 w.z = cvt_pk_bf16(siluf_fast(g1[0]) * u1[0], siluf_fast(g1[1]) * u1[1]); w.w = cvt_pk_bf16(siluf_fast(g1[2]) * u1[2], siluf_fast(g1[3]) * u1[3]);
;                 *(u32x4*)(O + r * ldo + col0) = w; }
; template <class Epi, class Sched, bool ALIGN_EPI = false, bool SP2 = false, bool KHOOK = false>
; __device__ __forceinline__ void gemm_phase(PG8_LAS unsigned char* lds, const Gemm g, const Sched& S, const Epi& E, const int tid_in) {
;     ...
;             PG8_LDB(B0, 0, 0); PG8_LDB(B1, 0, 1); PG8_SCHED; PG8_LDA(At, 0, 0); PG8_STAGE(PG8_SA(1, 1), a1 + hstep, voffA);
.LBB0_1066:
	s_add_u32 s64, s24, 0x80080
	s_addc_u32 s65, s13, 0
	v_lshl_add_u64 v[192:193], s[64:65], 0, v[132:133]
	s_add_i32 m0, s36, 0xc000
	s_nop 0
	global_load_lds_dwordx4 v[192:193], off
	v_lshl_add_u64 v[192:193], s[64:65], 0, v[134:135]
	s_add_i32 m0, s36, 0xe000
	s_nop 0
	global_load_lds_dwordx4 v[192:193], off
	s_mov_b32 s60, 1
	v_mul_f32_e32 v141, 0xbfb8aa3b, v126
	v_exp_f32_e32 v141, v141
	v_lshl_add_u32 v140, s18, 8, v136
	v_lshl_or_b32 v142, s19, 7, v138
	v_readlane_b32 s18, v254, 28
	v_add_f32_e32 v141, 1.0, v141
	v_rcp_f32_e32 v144, v141
	v_mul_f32_e32 v141, 0xbfb8aa3b, v127
	v_exp_f32_e32 v141, v141
	v_readlane_b32 s19, v254, 29
	v_ashrrev_i32_e32 v143, 31, v142
	s_movk_i32 s11, 0x2c00
	v_add_f32_e32 v141, 1.0, v141
	v_rcp_f32_e32 v145, v141
	s_andn2_b64 vcc, exec, s[14:15]
	v_pk_mul_f32 v[126:127], v[126:127], v[144:145]
	s_nop 0
	v_pk_mul_f32 v[122:123], v[122:123], v[126:127]
	s_nop 0
	v_cvt_pk_bf16_f32 v122, v122, v123
	v_mul_f32_e32 v123, 0xbfb8aa3b, v128
	v_exp_f32_e32 v123, v123
	s_nop 0
	v_add_f32_e32 v123, 1.0, v123
	v_rcp_f32_e32 v126, v123
	v_mul_f32_e32 v123, 0xbfb8aa3b, v129
	v_exp_f32_e32 v123, v123
	s_nop 0
	v_add_f32_e32 v123, 1.0, v123
	v_rcp_f32_e32 v127, v123
	s_nop 0
	v_pk_mul_f32 v[126:127], v[128:129], v[126:127]
	s_nop 0
	v_pk_mul_f32 v[124:125], v[124:125], v[126:127]
	s_nop 0
	v_cvt_pk_bf16_f32 v123, v124, v125
	v_mul_f32_e32 v124, 0xbfb8aa3b, v118
	v_mul_f32_e32 v125, 0xbfb8aa3b, v119
	v_exp_f32_e32 v124, v124
	v_exp_f32_e32 v125, v125
	v_add_f32_e32 v124, 1.0, v124
	v_add_f32_e32 v125, 1.0, v125
	v_rcp_f32_e32 v124, v124
	v_rcp_f32_e32 v125, v125
	s_nop 0
	v_pk_mul_f32 v[118:119], v[118:119], v[124:125]
	s_nop 0
	v_pk_mul_f32 v[114:115], v[114:115], v[118:119]
	s_nop 0
	v_cvt_pk_bf16_f32 v124, v114, v115
	v_mul_f32_e32 v114, 0xbfb8aa3b, v120
	v_mul_f32_e32 v115, 0xbfb8aa3b, v121
	v_exp_f32_e32 v114, v114
	v_exp_f32_e32 v115, v115
	v_add_f32_e32 v114, 1.0, v114
	v_add_f32_e32 v115, 1.0, v115
	v_rcp_f32_e32 v114, v114
	v_rcp_f32_e32 v115, v115
	s_nop 0
	v_pk_mul_f32 v[114:115], v[120:121], v[114:115]
	s_nop 0
	v_pk_mul_f32 v[114:115], v[116:117], v[114:115]
	v_lshlrev_b64 v[116:117], 1, v[142:143]
	v_cvt_pk_bf16_f32 v125, v114, v115
	v_mov_b64_e32 v[114:115], s[18:19]
	v_mad_i64_i32 v[118:119], s[18:19], v140, s11, v[114:115]
	v_lshl_add_u64 v[118:119], v[118:119], 0, v[116:117]
	global_store_dwordx4 v[118:119], v[122:125], off
	v_mul_f32_e32 v118, 0xbfb8aa3b, v110
	v_mul_f32_e32 v119, 0xbfb8aa3b, v111
	v_exp_f32_e32 v118, v118
	v_exp_f32_e32 v119, v119
	v_or_b32_e32 v120, 16, v140
	v_add_f32_e32 v118, 1.0, v118
	v_add_f32_e32 v119, 1.0, v119
	v_rcp_f32_e32 v118, v118
	v_rcp_f32_e32 v119, v119
	s_nop 0
	v_pk_mul_f32 v[110:111], v[110:111], v[118:119]
	s_nop 0
	v_pk_mul_f32 v[106:107], v[106:107], v[110:111]
	s_nop 0
	v_cvt_pk_bf16_f32 v106, v106, v107
	v_mul_f32_e32 v107, 0xbfb8aa3b, v112
	v_exp_f32_e32 v107, v107
	s_nop 0
	v_add_f32_e32 v107, 1.0, v107
	v_rcp_f32_e32 v110, v107
	v_mul_f32_e32 v107, 0xbfb8aa3b, v113
	v_exp_f32_e32 v107, v107
	s_nop 0
	v_add_f32_e32 v107, 1.0, v107
	v_rcp_f32_e32 v111, v107
	s_nop 0
	v_pk_mul_f32 v[110:111], v[112:113], v[110:111]
	s_nop 0
	v_pk_mul_f32 v[108:109], v[108:109], v[110:111]
	s_nop 0
	v_cvt_pk_bf16_f32 v107, v108, v109
	v_mul_f32_e32 v108, 0xbfb8aa3b, v102
	v_mul_f32_e32 v109, 0xbfb8aa3b, v103
	v_exp_f32_e32 v108, v108
	v_exp_f32_e32 v109, v109
	v_add_f32_e32 v108, 1.0, v108
	v_add_f32_e32 v109, 1.0, v109
	v_rcp_f32_e32 v108, v108
	v_rcp_f32_e32 v109, v109
	s_nop 0
	v_pk_mul_f32 v[102:103], v[102:103], v[108:109]
	s_nop 0
	v_pk_mul_f32 v[98:99], v[98:99], v[102:103]
	s_nop 0
	v_cvt_pk_bf16_f32 v108, v98, v99
	v_mul_f32_e32 v98, 0xbfb8aa3b, v104
	v_mul_f32_e32 v99, 0xbfb8aa3b, v105
	v_exp_f32_e32 v98, v98
	v_exp_f32_e32 v99, v99
	v_add_f32_e32 v98, 1.0, v98
	v_add_f32_e32 v99, 1.0, v99
	v_rcp_f32_e32 v98, v98
	v_rcp_f32_e32 v99, v99
	s_nop 0
	v_pk_mul_f32 v[98:99], v[104:105], v[98:99]
	s_nop 0
	v_pk_mul_f32 v[98:99], v[100:101], v[98:99]
	v_or_b32_e32 v100, 32, v140
	v_cvt_pk_bf16_f32 v109, v98, v99
	v_mad_i64_i32 v[98:99], s[18:19], v120, s11, v[114:115]
	v_lshl_add_u64 v[98:99], v[98:99], 0, v[116:117]
	global_store_dwordx4 v[98:99], v[106:109], off
	v_mul_f32_e32 v98, 0xbfb8aa3b, v94
	v_mul_f32_e32 v99, 0xbfb8aa3b, v95
	v_exp_f32_e32 v98, v98
	v_exp_f32_e32 v99, v99
	v_add_f32_e32 v98, 1.0, v98
	v_add_f32_e32 v99, 1.0, v99
	v_rcp_f32_e32 v98, v98
	v_rcp_f32_e32 v99, v99
	s_nop 0
	v_pk_mul_f32 v[94:95], v[94:95], v[98:99]
	s_nop 0
	v_pk_mul_f32 v[90:91], v[90:91], v[94:95]
	s_nop 0
	v_cvt_pk_bf16_f32 v90, v90, v91
	v_mul_f32_e32 v91, 0xbfb8aa3b, v96
	v_exp_f32_e32 v91, v91
	s_nop 0
	v_add_f32_e32 v91, 1.0, v91
	v_rcp_f32_e32 v94, v91
	v_mul_f32_e32 v91, 0xbfb8aa3b, v97
	v_exp_f32_e32 v91, v91
	s_nop 0
	v_add_f32_e32 v91, 1.0, v91
	v_rcp_f32_e32 v95, v91
	s_nop 0
	v_pk_mul_f32 v[94:95], v[96:97], v[94:95]
	s_nop 0
	v_pk_mul_f32 v[92:93], v[92:93], v[94:95]
	s_nop 0
	v_cvt_pk_bf16_f32 v91, v92, v93
	v_mul_f32_e32 v92, 0xbfb8aa3b, v86
	v_mul_f32_e32 v93, 0xbfb8aa3b, v87
	v_exp_f32_e32 v92, v92
	v_exp_f32_e32 v93, v93
	v_add_f32_e32 v92, 1.0, v92
	v_add_f32_e32 v93, 1.0, v93
	v_rcp_f32_e32 v92, v92
	v_rcp_f32_e32 v93, v93
	s_nop 0
	v_pk_mul_f32 v[86:87], v[86:87], v[92:93]
	s_nop 0
	v_pk_mul_f32 v[82:83], v[82:83], v[86:87]
	s_nop 0
	v_cvt_pk_bf16_f32 v92, v82, v83
	v_mul_f32_e32 v82, 0xbfb8aa3b, v88
	v_mul_f32_e32 v83, 0xbfb8aa3b, v89
	v_exp_f32_e32 v82, v82
	v_exp_f32_e32 v83, v83
	v_add_f32_e32 v82, 1.0, v82
	v_add_f32_e32 v83, 1.0, v83
	v_rcp_f32_e32 v82, v82
	v_rcp_f32_e32 v83, v83
	s_nop 0
	v_pk_mul_f32 v[82:83], v[88:89], v[82:83]
	s_nop 0
; __device__ __forceinline__ unsigned cvt_pk_bf16(float lo, float hi) { const f32x2_t v = {lo, hi}; const bf16x2_t c = __builtin_convertvector(v, bf16x2_t); return __builtin_bit_cast(unsigned, c); }
; __device__ __forceinline__ float siluf_fast(float x) { return x * sigmoidf_fast(x); }
;     __device__ __forceinline__ void operator()(const f32x4 (&acc)[2][2][4][2], const Unit& u, int wr, int wc, int fr, int fq) const {
;     ...
;             for (int m = 0; m < 4; ++m) { const size_t r = (size_t)(row0 + ai * HALF + m * 16);
;                 const f32x4 g0 = acc[ai][0][m][0], u0 = acc[ai][0][m][1], g1 = acc[ai][1][m][0], u1 = acc[ai][1][m][1];
;                 u32x4 w; w.x = cvt_pk_bf16(siluf_fast(g0[0]) * u0[0], siluf_fast(g0[1]) * u0[1]); w.y = cvt_pk_bf16(siluf_fast(g0[2]) * u0[2], siluf_fast(g0[3]) * u0[3]);
;                 w.z = cvt_pk_bf16(siluf_fast(g1[0]) * u1[0], siluf_fast(g1[1]) * u1[1]); w.w = cvt_pk_bf16(siluf_fast(g1[2]) * u1[2], siluf_fast(g1[3]) * u1[3]);
;                 *(u32x4*)(O + r * ldo + col0) = w; }
	v_pk_mul_f32 v[82:83], v[84:85], v[82:83]
	v_or_b32_e32 v84, 48, v140
	v_cvt_pk_bf16_f32 v93, v82, v83
	v_mad_i64_i32 v[82:83], s[18:19], v100, s11, v[114:115]
	v_lshl_add_u64 v[82:83], v[82:83], 0, v[116:117]
	global_store_dwordx4 v[82:83], v[90:93], off
	v_mul_f32_e32 v82, 0xbfb8aa3b, v78
	v_mul_f32_e32 v83, 0xbfb8aa3b, v79
	v_exp_f32_e32 v82, v82
	v_exp_f32_e32 v83, v83
	v_add_f32_e32 v82, 1.0, v82
	v_add_f32_e32 v83, 1.0, v83
	v_rcp_f32_e32 v82, v82
	v_rcp_f32_e32 v83, v83
	s_nop 0
	v_pk_mul_f32 v[78:79], v[78:79], v[82:83]
	s_nop 0
	v_pk_mul_f32 v[74:75], v[74:75], v[78:79]
	s_nop 0
	v_cvt_pk_bf16_f32 v74, v74, v75
	v_mul_f32_e32 v75, 0xbfb8aa3b, v80
	v_exp_f32_e32 v75, v75
	s_nop 0
	v_add_f32_e32 v75, 1.0, v75
	v_rcp_f32_e32 v78, v75
	v_mul_f32_e32 v75, 0xbfb8aa3b, v81
	v_exp_f32_e32 v75, v75
	s_nop 0
	v_add_f32_e32 v75, 1.0, v75
	v_rcp_f32_e32 v79, v75
	s_nop 0
	v_pk_mul_f32 v[78:79], v[80:81], v[78:79]
	s_nop 0
	v_pk_mul_f32 v[76:77], v[76:77], v[78:79]
	s_nop 0
	v_cvt_pk_bf16_f32 v75, v76, v77
	v_mul_f32_e32 v76, 0xbfb8aa3b, v70
	v_mul_f32_e32 v77, 0xbfb8aa3b, v71
	v_exp_f32_e32 v76, v76
	v_exp_f32_e32 v77, v77
	v_add_f32_e32 v76, 1.0, v76
	v_add_f32_e32 v77, 1.0, v77
	v_rcp_f32_e32 v76, v76
	v_rcp_f32_e32 v77, v77
	s_nop 0
	v_pk_mul_f32 v[70:71], v[70:71], v[76:77]
	s_nop 0
	v_pk_mul_f32 v[66:67], v[66:67], v[70:71]
	s_nop 0
	v_cvt_pk_bf16_f32 v76, v66, v67
	v_mul_f32_e32 v66, 0xbfb8aa3b, v72
	v_mul_f32_e32 v67, 0xbfb8aa3b, v73
	v_exp_f32_e32 v66, v66
	v_exp_f32_e32 v67, v67
	v_add_f32_e32 v66, 1.0, v66
	v_add_f32_e32 v67, 1.0, v67
	v_rcp_f32_e32 v66, v66
	v_rcp_f32_e32 v67, v67
	s_nop 0
	v_pk_mul_f32 v[66:67], v[72:73], v[66:67]
	s_nop 0
	v_pk_mul_f32 v[66:67], v[68:69], v[66:67]
	v_add_u32_e32 v68, 0x80, v140
	v_cvt_pk_bf16_f32 v77, v66, v67
	v_mad_i64_i32 v[66:67], s[18:19], v84, s11, v[114:115]
	v_lshl_add_u64 v[66:67], v[66:67], 0, v[116:117]
	global_store_dwordx4 v[66:67], v[74:77], off
	v_mul_f32_e32 v66, 0xbfb8aa3b, v62
	v_mul_f32_e32 v67, 0xbfb8aa3b, v63
	v_exp_f32_e32 v66, v66
	v_exp_f32_e32 v67, v67
	v_add_f32_e32 v66, 1.0, v66
	v_add_f32_e32 v67, 1.0, v67
	v_rcp_f32_e32 v66, v66
	v_rcp_f32_e32 v67, v67
	s_nop 0
	v_pk_mul_f32 v[62:63], v[62:63], v[66:67]
	s_nop 0
	v_pk_mul_f32 v[58:59], v[58:59], v[62:63]
	s_nop 0
	v_cvt_pk_bf16_f32 v58, v58, v59
	v_mul_f32_e32 v59, 0xbfb8aa3b, v64
	v_exp_f32_e32 v59, v59
	s_nop 0
	v_add_f32_e32 v59, 1.0, v59
	v_rcp_f32_e32 v62, v59
	v_mul_f32_e32 v59, 0xbfb8aa3b, v65
	v_exp_f32_e32 v59, v59
	s_nop 0
	v_add_f32_e32 v59, 1.0, v59
	v_rcp_f32_e32 v63, v59
	s_nop 0
	v_pk_mul_f32 v[62:63], v[64:65], v[62:63]
	s_nop 0
	v_pk_mul_f32 v[60:61], v[60:61], v[62:63]
	s_nop 0
	v_cvt_pk_bf16_f32 v59, v60, v61
	v_mul_f32_e32 v60, 0xbfb8aa3b, v54
	v_mul_f32_e32 v61, 0xbfb8aa3b, v55
	v_exp_f32_e32 v60, v60
	v_exp_f32_e32 v61, v61
	v_add_f32_e32 v60, 1.0, v60
	v_add_f32_e32 v61, 1.0, v61
	v_rcp_f32_e32 v60, v60
	v_rcp_f32_e32 v61, v61
	s_nop 0
	v_pk_mul_f32 v[54:55], v[54:55], v[60:61]
	s_nop 0
	v_pk_mul_f32 v[50:51], v[50:51], v[54:55]
	s_nop 0
	v_cvt_pk_bf16_f32 v60, v50, v51
	v_mul_f32_e32 v50, 0xbfb8aa3b, v56
	v_mul_f32_e32 v51, 0xbfb8aa3b, v57
	v_exp_f32_e32 v50, v50
	v_exp_f32_e32 v51, v51
	v_add_f32_e32 v50, 1.0, v50
	v_add_f32_e32 v51, 1.0, v51
	v_rcp_f32_e32 v50, v50
	v_rcp_f32_e32 v51, v51
	s_nop 0
	v_pk_mul_f32 v[50:51], v[56:57], v[50:51]
	s_nop 0
	v_pk_mul_f32 v[50:51], v[52:53], v[50:51]
	v_add_u32_e32 v52, 0x90, v140
	v_cvt_pk_bf16_f32 v61, v50, v51
	v_mad_i64_i32 v[50:51], s[18:19], v68, s11, v[114:115]
	v_lshl_add_u64 v[50:51], v[50:51], 0, v[116:117]
	global_store_dwordx4 v[50:51], v[58:61], off
	v_mul_f32_e32 v50, 0xbfb8aa3b, v46
	v_mul_f32_e32 v51, 0xbfb8aa3b, v47
	v_exp_f32_e32 v50, v50
	v_exp_f32_e32 v51, v51
	v_add_f32_e32 v50, 1.0, v50
	v_add_f32_e32 v51, 1.0, v51
	v_rcp_f32_e32 v50, v50
	v_rcp_f32_e32 v51, v51
	s_nop 0
	v_pk_mul_f32 v[46:47], v[46:47], v[50:51]
	s_nop 0
	v_pk_mul_f32 v[42:43], v[42:43], v[46:47]
	s_nop 0
	v_cvt_pk_bf16_f32 v42, v42, v43
	v_mul_f32_e32 v43, 0xbfb8aa3b, v48
	v_exp_f32_e32 v43, v43
	s_nop 0
	v_add_f32_e32 v43, 1.0, v43
	v_rcp_f32_e32 v46, v43
	v_mul_f32_e32 v43, 0xbfb8aa3b, v49
	v_exp_f32_e32 v43, v43
	s_nop 0
	v_add_f32_e32 v43, 1.0, v43
	v_rcp_f32_e32 v47, v43
	s_nop 0
	v_pk_mul_f32 v[46:47], v[48:49], v[46:47]
	s_nop 0
	v_pk_mul_f32 v[44:45], v[44:45], v[46:47]
	s_nop 0
; __device__ __forceinline__ unsigned cvt_pk_bf16(float lo, float hi) { const f32x2_t v = {lo, hi}; const bf16x2_t c = __builtin_convertvector(v, bf16x2_t); return __builtin_bit_cast(unsigned, c); }
; __device__ __forceinline__ float siluf_fast(float x) { return x * sigmoidf_fast(x); }
;     __device__ __forceinline__ void operator()(const f32x4 (&acc)[2][2][4][2], const Unit& u, int wr, int wc, int fr, int fq) const {
;     ...
;             for (int m = 0; m < 4; ++m) { const size_t r = (size_t)(row0 + ai * HALF + m * 16);
;                 const f32x4 g0 = acc[ai][0][m][0], u0 = acc[ai][0][m][1], g1 = acc[ai][1][m][0], u1 = acc[ai][1][m][1];
;                 u32x4 w; w.x = cvt_pk_bf16(siluf_fast(g0[0]) * u0[0], siluf_fast(g0[1]) * u0[1]); w.y = cvt_pk_bf16(siluf_fast(g0[2]) * u0[2], siluf_fast(g0[3]) * u0[3]);
;                 w.z = cvt_pk_bf16(siluf_fast(g1[0]) * u1[0], siluf_fast(g1[1]) * u1[1]); w.w = cvt_pk_bf16(siluf_fast(g1[2]) * u1[2], siluf_fast(g1[3]) * u1[3]);
;                 *(u32x4*)(O + r * ldo + col0) = w; }
; template <class Epi, class Sched, bool ALIGN_EPI = false, bool SP2 = false, bool KHOOK = false>
; __device__ __forceinline__ void gemm_phase(PG8_LAS unsigned char* lds, const Gemm g, const Sched& S, const Epi& E, const int tid_in) {
;     ...
;         if constexpr (!Epi::AFTER_DRAIN) { E(acc, cur, wr, wc, fr, fq); S.done(cur); }
;         if (!has_next) break;
	v_cvt_pk_bf16_f32 v43, v44, v45
	v_mul_f32_e32 v44, 0xbfb8aa3b, v38
	v_mul_f32_e32 v45, 0xbfb8aa3b, v39
	v_exp_f32_e32 v44, v44
	v_exp_f32_e32 v45, v45
	v_add_f32_e32 v44, 1.0, v44
	v_add_f32_e32 v45, 1.0, v45
	v_rcp_f32_e32 v44, v44
	v_rcp_f32_e32 v45, v45
	s_nop 0
	v_pk_mul_f32 v[38:39], v[38:39], v[44:45]
	s_nop 0
	v_pk_mul_f32 v[34:35], v[34:35], v[38:39]
	s_nop 0
	v_cvt_pk_bf16_f32 v44, v34, v35
	v_mul_f32_e32 v34, 0xbfb8aa3b, v40
	v_mul_f32_e32 v35, 0xbfb8aa3b, v41
	v_exp_f32_e32 v34, v34
	v_exp_f32_e32 v35, v35
	v_add_f32_e32 v34, 1.0, v34
	v_add_f32_e32 v35, 1.0, v35
	v_rcp_f32_e32 v34, v34
	v_rcp_f32_e32 v35, v35
	s_nop 0
	v_pk_mul_f32 v[34:35], v[40:41], v[34:35]
	s_nop 0
	v_pk_mul_f32 v[34:35], v[36:37], v[34:35]
	v_add_u32_e32 v36, 0xa0, v140
	v_cvt_pk_bf16_f32 v45, v34, v35
	v_mad_i64_i32 v[34:35], s[18:19], v52, s11, v[114:115]
	v_lshl_add_u64 v[34:35], v[34:35], 0, v[116:117]
	global_store_dwordx4 v[34:35], v[42:45], off
	v_mul_f32_e32 v34, 0xbfb8aa3b, v28
	v_mul_f32_e32 v35, 0xbfb8aa3b, v29
	v_exp_f32_e32 v34, v34
	v_exp_f32_e32 v35, v35
	v_add_f32_e32 v34, 1.0, v34
	v_add_f32_e32 v35, 1.0, v35
	v_rcp_f32_e32 v34, v34
	v_rcp_f32_e32 v35, v35
	s_nop 0
	v_pk_mul_f32 v[28:29], v[28:29], v[34:35]
	s_nop 0
	v_pk_mul_f32 v[24:25], v[24:25], v[28:29]
	s_nop 0
	v_cvt_pk_bf16_f32 v24, v24, v25
	v_mul_f32_e32 v25, 0xbfb8aa3b, v30
	v_exp_f32_e32 v25, v25
	s_nop 0
	v_add_f32_e32 v25, 1.0, v25
	v_rcp_f32_e32 v28, v25
	v_mul_f32_e32 v25, 0xbfb8aa3b, v31
	v_exp_f32_e32 v25, v25
	s_nop 0
	v_add_f32_e32 v25, 1.0, v25
	v_rcp_f32_e32 v29, v25
	s_nop 0
	v_pk_mul_f32 v[28:29], v[30:31], v[28:29]
	s_nop 0
	v_pk_mul_f32 v[26:27], v[26:27], v[28:29]
	s_nop 0
	v_cvt_pk_bf16_f32 v25, v26, v27
	v_mul_f32_e32 v26, 0xbfb8aa3b, v20
	v_mul_f32_e32 v27, 0xbfb8aa3b, v21
	v_exp_f32_e32 v26, v26
	v_exp_f32_e32 v27, v27
	v_add_f32_e32 v26, 1.0, v26
	v_add_f32_e32 v27, 1.0, v27
	v_rcp_f32_e32 v26, v26
	v_rcp_f32_e32 v27, v27
	s_nop 0
	v_pk_mul_f32 v[20:21], v[20:21], v[26:27]
	s_nop 0
	v_pk_mul_f32 v[16:17], v[16:17], v[20:21]
	s_nop 0
	v_cvt_pk_bf16_f32 v26, v16, v17
	v_mul_f32_e32 v16, 0xbfb8aa3b, v22
	v_mul_f32_e32 v17, 0xbfb8aa3b, v23
	v_exp_f32_e32 v16, v16
	v_exp_f32_e32 v17, v17
	v_add_f32_e32 v16, 1.0, v16
	v_add_f32_e32 v17, 1.0, v17
	v_rcp_f32_e32 v16, v16
	v_rcp_f32_e32 v17, v17
	s_nop 0
	v_pk_mul_f32 v[16:17], v[22:23], v[16:17]
	s_nop 0
	v_pk_mul_f32 v[16:17], v[18:19], v[16:17]
	v_add_u32_e32 v18, 0xb0, v140
	v_cvt_pk_bf16_f32 v27, v16, v17
	v_mad_i64_i32 v[16:17], s[18:19], v36, s11, v[114:115]
	v_lshl_add_u64 v[16:17], v[16:17], 0, v[116:117]
	global_store_dwordx4 v[16:17], v[24:27], off
	v_mul_f32_e32 v16, 0xbfb8aa3b, v12
	v_mul_f32_e32 v17, 0xbfb8aa3b, v13
	v_exp_f32_e32 v16, v16
	v_exp_f32_e32 v17, v17
	v_add_f32_e32 v16, 1.0, v16
	v_add_f32_e32 v17, 1.0, v17
	v_rcp_f32_e32 v16, v16
	v_rcp_f32_e32 v17, v17
	s_nop 0
	v_pk_mul_f32 v[12:13], v[12:13], v[16:17]
	s_nop 0
	v_pk_mul_f32 v[8:9], v[8:9], v[12:13]
	s_nop 0
	v_cvt_pk_bf16_f32 v8, v8, v9
	v_mul_f32_e32 v9, 0xbfb8aa3b, v14
	v_exp_f32_e32 v9, v9
	s_nop 0
	v_add_f32_e32 v9, 1.0, v9
	v_rcp_f32_e32 v12, v9
	v_mul_f32_e32 v9, 0xbfb8aa3b, v15
	v_exp_f32_e32 v9, v9
	s_nop 0
	v_add_f32_e32 v9, 1.0, v9
	v_rcp_f32_e32 v13, v9
	s_nop 0
	v_pk_mul_f32 v[12:13], v[14:15], v[12:13]
	s_nop 0
	v_pk_mul_f32 v[10:11], v[10:11], v[12:13]
	s_nop 0
	v_cvt_pk_bf16_f32 v9, v10, v11
	v_mul_f32_e32 v10, 0xbfb8aa3b, v4
	v_mul_f32_e32 v11, 0xbfb8aa3b, v5
	v_exp_f32_e32 v10, v10
	v_exp_f32_e32 v11, v11
	v_add_f32_e32 v10, 1.0, v10
	v_add_f32_e32 v11, 1.0, v11
	v_rcp_f32_e32 v10, v10
	v_rcp_f32_e32 v11, v11
	s_nop 0
	v_pk_mul_f32 v[4:5], v[4:5], v[10:11]
	s_nop 0
	v_pk_mul_f32 v[0:1], v[0:1], v[4:5]
	s_nop 0
	v_cvt_pk_bf16_f32 v10, v0, v1
	v_mul_f32_e32 v0, 0xbfb8aa3b, v6
	v_mul_f32_e32 v1, 0xbfb8aa3b, v7
	v_exp_f32_e32 v0, v0
	v_exp_f32_e32 v1, v1
	v_add_f32_e32 v0, 1.0, v0
	v_add_f32_e32 v1, 1.0, v1
	v_rcp_f32_e32 v0, v0
	v_rcp_f32_e32 v1, v1
	s_nop 0
	v_pk_mul_f32 v[0:1], v[6:7], v[0:1]
	s_nop 0
	v_pk_mul_f32 v[0:1], v[2:3], v[0:1]
	s_nop 0
	v_cvt_pk_bf16_f32 v11, v0, v1
	v_mad_i64_i32 v[0:1], s[18:19], v18, s11, v[114:115]
	v_lshl_add_u64 v[0:1], v[0:1], 0, v[116:117]
	s_mov_b64 s[18:19], -1
	global_store_dwordx4 v[0:1], v[8:11], off
	s_cbranch_vccnz .LBB0_1058
	s_andn2_b64 vcc, exec, s[0:1]
	s_cbranch_vccnz .LBB0_1057
	s_barrier
	s_branch .LBB0_1057
